# seam P12->P13: counter-based split arrive/wait instead of the grid barrier; last row phase rebalanced (10 rows/wave on workgroups 64-255, 2 rows/wave on the split-K workgroups 0-63)
# speedup vs baseline: 1.0171x; 1.0002x over previous
; __device__ __forceinline__ unsigned cvt_pk_bf16(float lo, float hi) { const f32x2_t v = {lo, hi}; const bf16x2_t b = __builtin_convertvector(v, bf16x2_t); return __builtin_bit_cast(unsigned, b); }
;     __device__ __forceinline__ void operator()(const f32x4 (&acc)[2][2][4][2], const Unit& u, int wr, int wc, int fr, int fq) const {
;         if (u.atomic == 0) {
;             const __amdgpu_buffer_rsrc_t rs = __builtin_amdgcn_make_buffer_rsrc(C, 0, 0x7ffffff0, 0x00020000);
;             const int row0 = u.pm * BM + wr * 64 + fr; const int col0 = u.pn * BM + wc * 32 + 8 * fq;
; #pragma unroll
;             for (int ai = 0; ai < 2; ++ai)
; #pragma unroll
;                 for (int m = 0; m < 4; ++m) { const unsigned ro = (unsigned)((row0 + ai * HALF + m * 16) * ldc + col0) * 2u;
; #pragma unroll
;                     for (int bj = 0; bj < 2; ++bj) { const f32x4 v0 = acc[ai][bj][m][0], v1 = acc[ai][bj][m][1];
;                         u32x4 w; w.x = cvt_pk_bf16(v0[0], v0[1]); w.y = cvt_pk_bf16(v0[2], v0[3]); w.z = cvt_pk_bf16(v1[0], v1[1]); w.w = cvt_pk_bf16(v1[2], v1[3]);
;                         __builtin_amdgcn_raw_buffer_store_b128(w, rs, ro + bj * HALF * 2, 0, 16); } }
.LBB0_1078:
.LBB0_1079:
	s_lshl_b32 s18, s70, 8
	v_lshl_add_u32 v136, s50, 8, v142
	v_lshl_or_b32 v142, v148, 3, s18
	v_or_b32_e32 v142, s45, v142
	v_lshlrev_b32_e32 v143, 11, v136
	v_lshl_add_u32 v143, v142, 1, v143
	v_cvt_pk_bf16_f32 v108, v108, v109
	v_cvt_pk_bf16_f32 v109, v110, v111
	v_cvt_pk_bf16_f32 v110, v104, v105
	v_cvt_pk_bf16_f32 v111, v106, v107
	v_lshlrev_b32_e32 v104, 10, v136
	buffer_store_dwordx4 v[108:111], v143, s[4:7], 0 offen offset:256 sc1
	v_cvt_pk_bf16_f32 v124, v124, v125
	v_cvt_pk_bf16_f32 v125, v126, v127
	v_add_lshl_u32 v108, v104, v142, 1
	v_cvt_pk_bf16_f32 v126, v120, v121
	v_cvt_pk_bf16_f32 v127, v122, v123
	v_add_u32_e32 v109, 0x8000, v108
	v_cvt_pk_bf16_f32 v92, v92, v93
	v_cvt_pk_bf16_f32 v93, v94, v95
	v_cvt_pk_bf16_f32 v94, v88, v89
	v_cvt_pk_bf16_f32 v95, v90, v91
	buffer_store_dwordx4 v[124:127], v143, s[4:7], 0 offen sc1
	v_cvt_pk_bf16_f32 v104, v116, v117
	v_cvt_pk_bf16_f32 v105, v118, v119
	v_cvt_pk_bf16_f32 v106, v112, v113
	v_cvt_pk_bf16_f32 v107, v114, v115
	buffer_store_dwordx4 v[92:95], v109, s[4:7], 0 offen offset:256 sc1
	v_cvt_pk_bf16_f32 v76, v76, v77
	v_cvt_pk_bf16_f32 v77, v78, v79
	v_add_u32_e32 v92, 0x10000, v108
	v_cvt_pk_bf16_f32 v78, v72, v73
	v_cvt_pk_bf16_f32 v79, v74, v75
	buffer_store_dwordx4 v[104:107], v109, s[4:7], 0 offen sc1
	v_cvt_pk_bf16_f32 v88, v100, v101
	v_cvt_pk_bf16_f32 v89, v102, v103
	v_cvt_pk_bf16_f32 v90, v96, v97
	v_cvt_pk_bf16_f32 v91, v98, v99
	buffer_store_dwordx4 v[76:79], v92, s[4:7], 0 offen offset:256 sc1
	v_cvt_pk_bf16_f32 v72, v84, v85
	v_cvt_pk_bf16_f32 v73, v86, v87
	v_add_u32_e32 v76, 0x18000, v108
	v_cvt_pk_bf16_f32 v74, v80, v81
	v_cvt_pk_bf16_f32 v75, v82, v83
	v_cvt_pk_bf16_f32 v68, v68, v69
	v_cvt_pk_bf16_f32 v69, v70, v71
	v_cvt_pk_bf16_f32 v70, v64, v65
	v_cvt_pk_bf16_f32 v71, v66, v67
	v_add_u32_e32 v64, 0x40000, v108
	v_cvt_pk_bf16_f32 v44, v44, v45
	v_cvt_pk_bf16_f32 v45, v46, v47
	v_cvt_pk_bf16_f32 v46, v40, v41
	v_cvt_pk_bf16_f32 v47, v42, v43
	buffer_store_dwordx4 v[88:91], v92, s[4:7], 0 offen sc1
	buffer_store_dwordx4 v[72:75], v76, s[4:7], 0 offen sc1
	buffer_store_dwordx4 v[68:71], v76, s[4:7], 0 offen offset:256 sc1
	v_cvt_pk_bf16_f32 v60, v60, v61
	v_cvt_pk_bf16_f32 v61, v62, v63
	v_cvt_pk_bf16_f32 v62, v56, v57
	v_cvt_pk_bf16_f32 v63, v58, v59
	buffer_store_dwordx4 v[44:47], v64, s[4:7], 0 offen offset:256 sc1
	v_cvt_pk_bf16_f32 v28, v28, v29
	v_cvt_pk_bf16_f32 v29, v30, v31
	v_add_u32_e32 v44, 0x48000, v108
	v_cvt_pk_bf16_f32 v30, v24, v25
	v_cvt_pk_bf16_f32 v31, v26, v27
	buffer_store_dwordx4 v[60:63], v64, s[4:7], 0 offen sc1
	v_cvt_pk_bf16_f32 v40, v52, v53
	v_cvt_pk_bf16_f32 v41, v54, v55
	v_cvt_pk_bf16_f32 v42, v48, v49
	v_cvt_pk_bf16_f32 v43, v50, v51
	buffer_store_dwordx4 v[28:31], v44, s[4:7], 0 offen offset:256 sc1
	v_cvt_pk_bf16_f32 v12, v12, v13
	v_cvt_pk_bf16_f32 v13, v14, v15
	v_add_u32_e32 v28, 0x50000, v108
	v_cvt_pk_bf16_f32 v14, v8, v9
	v_cvt_pk_bf16_f32 v15, v10, v11
	buffer_store_dwordx4 v[40:43], v44, s[4:7], 0 offen sc1
	v_cvt_pk_bf16_f32 v24, v36, v37
	v_cvt_pk_bf16_f32 v25, v38, v39
	v_cvt_pk_bf16_f32 v26, v32, v33
	v_cvt_pk_bf16_f32 v27, v34, v35
	buffer_store_dwordx4 v[12:15], v28, s[4:7], 0 offen offset:256 sc1
	v_cvt_pk_bf16_f32 v8, v20, v21
	v_cvt_pk_bf16_f32 v9, v22, v23
	v_add_u32_e32 v12, 0x58000, v108
	v_cvt_pk_bf16_f32 v10, v16, v17
	v_cvt_pk_bf16_f32 v11, v18, v19
	v_cvt_pk_bf16_f32 v4, v4, v5
	v_cvt_pk_bf16_f32 v5, v6, v7
	v_cvt_pk_bf16_f32 v6, v0, v1
	v_cvt_pk_bf16_f32 v7, v2, v3
	buffer_store_dwordx4 v[24:27], v28, s[4:7], 0 offen sc1
	buffer_store_dwordx4 v[8:11], v12, s[4:7], 0 offen sc1
	buffer_store_dwordx4 v[4:7], v12, s[4:7], 0 offen offset:256 sc1
	s_waitcnt vmcnt(0)
	s_barrier
	s_barrier
	s_cmp_lg_u32 s33, 0
	s_cbranch_scc1 .Lseam_arrF_done
	v_mbcnt_lo_u32_b32 v0, -1, 0
	v_mbcnt_hi_u32_b32 v0, -1, v0
	v_cmp_eq_u32_e32 vcc, 0, v0
	s_and_saveexec_b64 s[100:101], vcc
	v_mov_b32_e32 v0, 0x3800
	v_mov_b32_e32 v1, 1
	global_atomic_add v0, v1, s[2:3]
	s_mov_b64 exec, s[100:101]
.Lseam_arrF_done:
	s_branch .LBB0_1069
.LBB0_1080:
	s_waitcnt vmcnt(0)
	s_cmpk_gt_u32 s28, 0xff
	s_cbranch_scc1 .LBB0_1082
	s_barrier

; __device__ __forceinline__ int fresh_tid(int wv) { int l; asm volatile("v_mbcnt_lo_u32_b32 %0, -1, 0\n\tv_mbcnt_hi_u32_b32 %0, -1, %0" : "=v"(l)); return wv * 64 + l; }
; #define LAS __attribute__((address_space(3)))
; __device__ __forceinline__ unsigned xb_add(unsigned* p, unsigned v) { return __hip_atomic_fetch_add(p, v, __ATOMIC_RELAXED, __HIP_MEMORY_SCOPE_AGENT); }
; __device__ __forceinline__ unsigned xb_xcc_id() { return (unsigned)__builtin_amdgcn_s_getreg((3 << 11) | 20) & 0xFu; }
; #define GSYNC() do { for (int r_ = 0; r_ < REP_SYNC; ++r_) xcd_barrier((unsigned*)ws, (volatile LAS unsigned*)(lds + LDS_BYTES - 16), wv); FRESH(); } while (0)
; __device__ __forceinline__ void xcd_barrier(unsigned* barw, volatile LAS unsigned* stw, const int wv) {
;     XcdBarrier b; b.bar = barw; b.x = xb_xcc_id(); b.st = stw;
;     asm volatile("s_waitcnt vmcnt(0)" ::: "memory");
;     __syncthreads();
;     if (fresh_tid(wv) == 0) {
;         unsigned* bar = b.bar;
;         __builtin_amdgcn_s_waitcnt(0);
;         unsigned nloc = b.st[0], nx = b.st[1];
;         if (nloc == 0u) { xcd_barrier_complete(bar, b.x, nloc, nx); b.st[0] = nloc; b.st[1] = nx; }
;         const unsigned old = xb_add(&bar[XB_XSUB(b.x)], 1u);
;         const unsigned gen = old / nloc;
;         if (old + 1u == (gen + 1u) * nloc) {
; __global__ void __launch_bounds__(512, 2) hymba_mega(Params P_unused) {
;     ...
;     GSYNC();
.LBB0_1083:
	s_getreg_b32 s6, hwreg(HW_REG_XCC_ID, 0, 4)
	s_waitcnt vmcnt(0)
	s_waitcnt vmcnt(0) lgkmcnt(0)
	s_barrier
	v_mbcnt_lo_u32_b32 v0, -1, 0
	v_mbcnt_hi_u32_b32 v0, -1, v0
	s_nop 0
	v_cmp_eq_u32_e32 vcc, s74, v0
	s_and_saveexec_b64 s[0:1], vcc
	s_cbranch_execz .LBB0_1135
	s_cmp_lt_u32 s73, 0x200
	s_cbranch_scc0 .Lseam_nosplit
	buffer_wbl2 sc1
	s_waitcnt vmcnt(0)
	v_mov_b32_e32 v0, 0x3900
	v_mov_b32_e32 v1, 1
	global_atomic_add v0, v1, s[2:3]
.Lseam_nosplit:
	v_mov_b32_e32 v0, 0x3800
	s_mov_b32 s98, 0
.Lseam_pollF:
	global_load_dword v1, v0, s[2:3] sc1
	s_add_u32 s98, s98, 1
	s_waitcnt vmcnt(0)
	v_readfirstlane_b32 s99, v1
	s_cmp_ge_u32 s99, 0x100
	s_cbranch_scc1 .Lseam_F_ok
	s_cmp_lt_u32 s98, 0x4000
	s_cbranch_scc1 .Lseam_pollF

; __device__ __forceinline__ int fresh_tid(int wv) { int l; asm volatile("v_mbcnt_lo_u32_b32 %0, -1, 0\n\tv_mbcnt_hi_u32_b32 %0, -1, %0" : "=v"(l)); return wv * 64 + l; }
; #define LAS __attribute__((address_space(3)))
; __device__ __forceinline__ void rows_load(PR P, const int mode, const int row, const int lane, RowRaw& R) {
;     if (mode <= 1) { const float* xin = P.x_prompt + (size_t)row * 1024;
; #pragma unroll
;         for (int q = 0; q < 4; ++q) { const f32x4 t_ = __builtin_nontemporal_load((const f32x4*)(xin + (q * 64 + lane) * 4)); R.xf[q] = make_float4(t_[0], t_[1], t_[2], t_[3]); } }
;     else { const bf16_t* xb = (mode == 2 ? (const bf16_t*)P.out : (const bf16_t*)(P.ws + WS_FO + 34603008)) + (size_t)row * 1024;
; #pragma unroll
;         for (int q = 0; q < 4; ++q) R.xb[q] = __builtin_nontemporal_load((const u32x2*)(xb + (q * 64 + lane) * 4)); }
;     if (mode != 0) { const bf16_t* FO = (const bf16_t*)(P.ws + WS_FO) + (size_t)row * 1024;
; #pragma unroll
;         for (int q = 0; q < 4; ++q) R.fb[q] = __builtin_nontemporal_load((const u32x2*)(FO + (q * 64 + lane) * 4)); }
; }
; __device__ __forceinline__ void rows_phase(PR P, const int mode, LAS float* ldsf, const int wv) {
;     const int tid = fresh_tid(wv); const int lane = tid & 63; const int gw = blockIdx.x * 8 + (tid >> 6), nw = gridDim.x * 8;
;     const float* gpost = P.norm_g + (mode == 1 ? 1 : (mode == 2 ? 3 : 5)) * 1024;
;     const float* gnext = P.norm_g + (mode == 0 ? 0 : (mode == 1 ? 2 : 4)) * 1024;
;     float4 gp[4], gn[4];
; #pragma unroll
;     for (int q = 0; q < 4; ++q) { gp[q] = *(const float4*)(gpost + (q * 64 + lane) * 4); gn[q] = *(const float4*)(gnext + (q * 64 + lane) * 4); }
;     if (gw < MP) {
;         const int last = gw + ((MP - 1 - gw) / nw) * nw;
;         RowRaw R, N;
;         rows_load(P, mode, gw, lane, R);
;         for (int row = gw; row < MP; row += nw) {
;             const int nrow = row + nw < MP ? row + nw : last;
;             rows_load(P, mode, nrow, lane, N);
.LBB0_1135:
	s_or_b64 exec, exec, s[0:1]
	s_waitcnt lgkmcnt(0)
	s_barrier
	v_mbcnt_lo_u32_b32 v0, -1, 0
	v_mbcnt_hi_u32_b32 v0, -1, v0
	s_load_dwordx2 s[0:1], s[38:39], 0x28
	v_add_u32_e32 v17, s33, v0
	v_and_b32_e32 v43, 63, v0
	v_ashrrev_i32_e32 v42, 6, v17
	v_lshlrev_b32_e32 v44, 2, v43
	s_waitcnt lgkmcnt(0)
	s_add_u32 s4, s0, 0x5000
	v_add_u32_e32 v18, s73, v42
	s_movk_i32 s8, 0x4000
	s_addc_u32 s5, s1, 0
	v_mov_b32_e32 v23, 0
	v_cmp_gt_i32_e32 vcc, s8, v18
	v_lshlrev_b32_e32 v16, 2, v44
	s_and_saveexec_b64 s[0:1], vcc
	s_xor_b64 s[6:7], exec, s[0:1]
	s_cbranch_execz .LBB0_1139
	s_cmp_lt_u32 s73, 0x200
	s_cbranch_scc1 .Lp13_low
	global_load_dwordx4 v[0:3], v16, s[4:5]
	global_load_dwordx4 v[4:7], v16, s[4:5] offset:1024
	global_load_dwordx4 v[8:11], v16, s[4:5] offset:2048
	global_load_dwordx4 v[12:15], v16, s[4:5] offset:3072
	s_load_dwordx4 s[0:3], s[38:39], 0xd0
	s_lshr_b32 s22, s33, 6
	s_add_i32 s22, s22, s73
	s_sub_u32 s22, s22, 512
	s_lshl_b32 s23, s22, 11
	v_lshl_add_u32 v18, v43, 3, s23
	s_lshl_b32 s23, s22, 12
	v_lshl_add_u32 v19, v43, 4, s23
	v_mov_b32_e32 v226, 0x358637bd
	s_waitcnt lgkmcnt(0)
	s_add_u32 s8, s2, 0xb904800
	s_addc_u32 s9, s3, 0
	s_add_u32 s10, s2, 0x9804800
	s_addc_u32 s11, s3, 0
	s_mov_b64 s[12:13], s[8:9]
	s_mov_b64 s[14:15], s[10:11]
	global_load_dwordx2 v[64:65], v18, s[12:13] offset:0 nt
	global_load_dwordx2 v[66:67], v18, s[12:13] offset:512 nt
	global_load_dwordx2 v[68:69], v18, s[12:13] offset:1024 nt
	global_load_dwordx2 v[70:71], v18, s[12:13] offset:1536 nt
	global_load_dwordx2 v[72:73], v18, s[14:15] offset:0 nt
	global_load_dwordx2 v[74:75], v18, s[14:15] offset:512 nt
	global_load_dwordx2 v[76:77], v18, s[14:15] offset:1024 nt
	global_load_dwordx2 v[78:79], v18, s[14:15] offset:1536 nt
	s_add_u32 s12, s12, 0x300000
	s_addc_u32 s13, s13, 0
	s_add_u32 s14, s14, 0x300000
	s_addc_u32 s15, s15, 0
	global_load_dwordx2 v[80:81], v18, s[12:13] offset:0 nt
	global_load_dwordx2 v[82:83], v18, s[12:13] offset:512 nt
	global_load_dwordx2 v[84:85], v18, s[12:13] offset:1024 nt
	global_load_dwordx2 v[86:87], v18, s[12:13] offset:1536 nt
	global_load_dwordx2 v[88:89], v18, s[14:15] offset:0 nt
	global_load_dwordx2 v[90:91], v18, s[14:15] offset:512 nt
	global_load_dwordx2 v[92:93], v18, s[14:15] offset:1024 nt
	global_load_dwordx2 v[94:95], v18, s[14:15] offset:1536 nt
	s_add_u32 s12, s12, 0x300000
	s_addc_u32 s13, s13, 0
	s_add_u32 s14, s14, 0x300000
	s_addc_u32 s15, s15, 0
	global_load_dwordx2 v[96:97], v18, s[12:13] offset:0 nt
	global_load_dwordx2 v[98:99], v18, s[12:13] offset:512 nt
	global_load_dwordx2 v[100:101], v18, s[12:13] offset:1024 nt
	global_load_dwordx2 v[102:103], v18, s[12:13] offset:1536 nt
	global_load_dwordx2 v[104:105], v18, s[14:15] offset:0 nt
	global_load_dwordx2 v[106:107], v18, s[14:15] offset:512 nt
	global_load_dwordx2 v[108:109], v18, s[14:15] offset:1024 nt
	global_load_dwordx2 v[110:111], v18, s[14:15] offset:1536 nt
	s_add_u32 s12, s12, 0x300000
	s_addc_u32 s13, s13, 0
	s_add_u32 s14, s14, 0x300000
	s_addc_u32 s15, s15, 0
	global_load_dwordx2 v[112:113], v18, s[12:13] offset:0 nt
	global_load_dwordx2 v[114:115], v18, s[12:13] offset:512 nt
	global_load_dwordx2 v[116:117], v18, s[12:13] offset:1024 nt
	global_load_dwordx2 v[118:119], v18, s[12:13] offset:1536 nt
	global_load_dwordx2 v[120:121], v18, s[14:15] offset:0 nt
	global_load_dwordx2 v[122:123], v18, s[14:15] offset:512 nt
	global_load_dwordx2 v[124:125], v18, s[14:15] offset:1024 nt
	global_load_dwordx2 v[126:127], v18, s[14:15] offset:1536 nt
	s_add_u32 s12, s12, 0x300000
	s_addc_u32 s13, s13, 0
	s_add_u32 s14, s14, 0x300000
	s_addc_u32 s15, s15, 0
	global_load_dwordx2 v[128:129], v18, s[12:13] offset:0 nt
	global_load_dwordx2 v[130:131], v18, s[12:13] offset:512 nt
	global_load_dwordx2 v[132:133], v18, s[12:13] offset:1024 nt
	global_load_dwordx2 v[134:135], v18, s[12:13] offset:1536 nt
	global_load_dwordx2 v[136:137], v18, s[14:15] offset:0 nt
	global_load_dwordx2 v[138:139], v18, s[14:15] offset:512 nt
	global_load_dwordx2 v[140:141], v18, s[14:15] offset:1024 nt
	global_load_dwordx2 v[142:143], v18, s[14:15] offset:1536 nt
	s_add_u32 s12, s12, 0x300000
	s_addc_u32 s13, s13, 0
	s_add_u32 s14, s14, 0x300000
	s_addc_u32 s15, s15, 0
	global_load_dwordx2 v[144:145], v18, s[12:13] offset:0 nt
	global_load_dwordx2 v[146:147], v18, s[12:13] offset:512 nt
	global_load_dwordx2 v[148:149], v18, s[12:13] offset:1024 nt
	global_load_dwordx2 v[150:151], v18, s[12:13] offset:1536 nt
	global_load_dwordx2 v[152:153], v18, s[14:15] offset:0 nt
	global_load_dwordx2 v[154:155], v18, s[14:15] offset:512 nt
	global_load_dwordx2 v[156:157], v18, s[14:15] offset:1024 nt
	global_load_dwordx2 v[158:159], v18, s[14:15] offset:1536 nt
	s_waitcnt vmcnt(40)
; __device__ __forceinline__ unsigned cvt_pk_bf16(float lo, float hi) { const f32x2_t v = {lo, hi}; const bf16x2_t b = __builtin_convertvector(v, bf16x2_t); return __builtin_bit_cast(unsigned, b); }
; __device__ __forceinline__ float lo_bf(unsigned x) { return __uint_as_float(x << 16); }
; __device__ __forceinline__ float hi_bf(unsigned x) { return __uint_as_float(x & 0xffff0000u); }
; __device__ __forceinline__ void rows_proc(PR P, const int mode, const int row, const int lane, float4 (&xv)[4], const float4 (&fo)[4], const float4 (&gp)[4], const float4 (&gn)[4]) {
;     bf16_t* XN = (bf16_t*)(P.ws + WS_XN);
;     if (mode != 0) {
;         float ss = 0.f;
; #pragma unroll
;         for (int q = 0; q < 4; ++q) ss += fo[q].x * fo[q].x + fo[q].y * fo[q].y + fo[q].z * fo[q].z + fo[q].w * fo[q].w;
;         ss = wave_sum(ss); const float r = rsqrtf(ss * (1.0f / 1024.0f) + 1e-6f) * (mode == 2 ? 1.0f : 0.5f);
; #pragma unroll
;         for (int q = 0; q < 4; ++q) {
;             xv[q].x += fo[q].x * r * gp[q].x; xv[q].y += fo[q].y * r * gp[q].y; xv[q].z += fo[q].z * r * gp[q].z; xv[q].w += fo[q].w * r * gp[q].w;
;             if (mode == 3) { const f32x4 t_ = {xv[q].x, xv[q].y, xv[q].z, xv[q].w}; __builtin_nontemporal_store(t_, (f32x4*)(P.out + (size_t)row * 1024 + (q * 64 + lane) * 4)); }
;             else { bf16_t* xo = (mode == 1 ? (bf16_t*)P.out : (bf16_t*)(P.ws + WS_FO + 34603008)) + (size_t)row * 1024; u32x2 t; t.x = pg8::cvt_pk_bf16(xv[q].x, xv[q].y); t.y = pg8::cvt_pk_bf16(xv[q].z, xv[q].w);
;                 __builtin_nontemporal_store(t, (u32x2*)(xo + (q * 64 + lane) * 4)); } }
;         if (mode == 3) return;
; __device__ __forceinline__ void rows_phase(PR P, const int mode, LAS float* ldsf, const int wv) {
;     ...
;         for (int row = gw; row < MP; row += nw) {
;             const int nrow = row + nw < MP ? row + nw : last;
;             rows_load(P, mode, nrow, lane, N);
;             float4 xv[4], fo[4];
; #pragma unroll
;             for (int q = 0; q < 4; ++q) {
;                 xv[q] = mode <= 1 ? R.xf[q] : make_float4(lo_bf(R.xb[q].x), hi_bf(R.xb[q].x), lo_bf(R.xb[q].y), hi_bf(R.xb[q].y));
;                 fo[q] = make_float4(lo_bf(R.fb[q].x), hi_bf(R.fb[q].x), lo_bf(R.fb[q].y), hi_bf(R.fb[q].y)); }
;             rows_proc(P, mode, row, lane, xv, fo, gp, gn);
;             R = N;
;         }
	v_lshlrev_b32_e32 v208, 16, v72
	v_and_b32_e32 v209, 0xffff0000, v72
	v_lshlrev_b32_e32 v210, 16, v73
	v_and_b32_e32 v211, 0xffff0000, v73
	v_lshlrev_b32_e32 v212, 16, v74
	v_and_b32_e32 v213, 0xffff0000, v74
	v_lshlrev_b32_e32 v214, 16, v75
	v_and_b32_e32 v215, 0xffff0000, v75
	v_lshlrev_b32_e32 v216, 16, v76
	v_and_b32_e32 v217, 0xffff0000, v76
	v_lshlrev_b32_e32 v218, 16, v77
	v_and_b32_e32 v219, 0xffff0000, v77
	v_lshlrev_b32_e32 v220, 16, v78
	v_and_b32_e32 v221, 0xffff0000, v78
	v_lshlrev_b32_e32 v222, 16, v79
	v_and_b32_e32 v223, 0xffff0000, v79
	v_pk_mul_f32 v[224:225], v[208:209], v[208:209]
	v_pk_fma_f32 v[224:225], v[210:211], v[210:211], v[224:225]
	v_pk_fma_f32 v[224:225], v[212:213], v[212:213], v[224:225]
	v_pk_fma_f32 v[224:225], v[214:215], v[214:215], v[224:225]
	v_pk_fma_f32 v[224:225], v[216:217], v[216:217], v[224:225]
	v_pk_fma_f32 v[224:225], v[218:219], v[218:219], v[224:225]
	v_pk_fma_f32 v[224:225], v[220:221], v[220:221], v[224:225]
	v_pk_fma_f32 v[224:225], v[222:223], v[222:223], v[224:225]
	v_add_f32_e32 v224, v224, v225
	v_lshlrev_b32_e32 v192, 16, v64
	v_and_b32_e32 v193, 0xffff0000, v64
	v_lshlrev_b32_e32 v194, 16, v65
	v_and_b32_e32 v195, 0xffff0000, v65
	v_add_f32_dpp v224, v224, v224 quad_perm:[1,0,3,2] row_mask:0xf bank_mask:0xf bound_ctrl:1
	v_lshlrev_b32_e32 v196, 16, v66
	v_and_b32_e32 v197, 0xffff0000, v66
	v_lshlrev_b32_e32 v198, 16, v67
	v_and_b32_e32 v199, 0xffff0000, v67
	v_add_f32_dpp v224, v224, v224 quad_perm:[2,3,0,1] row_mask:0xf bank_mask:0xf bound_ctrl:1
	v_lshlrev_b32_e32 v200, 16, v68
	v_and_b32_e32 v201, 0xffff0000, v68
	v_lshlrev_b32_e32 v202, 16, v69
	v_and_b32_e32 v203, 0xffff0000, v69
	v_add_f32_dpp v224, v224, v224 row_half_mirror row_mask:0xf bank_mask:0xf bound_ctrl:1
	v_lshlrev_b32_e32 v204, 16, v70
	v_and_b32_e32 v205, 0xffff0000, v70
	v_lshlrev_b32_e32 v206, 16, v71
	v_and_b32_e32 v207, 0xffff0000, v71
	v_add_f32_dpp v224, v224, v224 row_mirror row_mask:0xf bank_mask:0xf bound_ctrl:1
	s_nop 0
	v_readlane_b32 s16, v224, 0
	v_readlane_b32 s17, v224, 16
	v_readlane_b32 s18, v224, 32
	v_readlane_b32 s19, v224, 48
	s_nop 1
	v_mov_b32_e32 v224, s17
	v_add_f32_e32 v224, s16, v224
	v_add_f32_e32 v224, s18, v224
	v_add_f32_e32 v224, s19, v224
	v_fmamk_f32 v224, v224, 0x3a800000, v226
	v_rsq_f32_e32 v224, v224
	s_nop 0
	v_mul_f32_e32 v224, 0.5, v224
	v_pk_mul_f32 v[208:209], v[224:225], v[208:209] op_sel_hi:[0,1]
	v_pk_mul_f32 v[210:211], v[224:225], v[210:211] op_sel_hi:[0,1]
	v_pk_mul_f32 v[212:213], v[224:225], v[212:213] op_sel_hi:[0,1]
	v_pk_mul_f32 v[214:215], v[224:225], v[214:215] op_sel_hi:[0,1]
	v_pk_mul_f32 v[216:217], v[224:225], v[216:217] op_sel_hi:[0,1]
	v_pk_mul_f32 v[218:219], v[224:225], v[218:219] op_sel_hi:[0,1]
	v_pk_mul_f32 v[220:221], v[224:225], v[220:221] op_sel_hi:[0,1]
	v_pk_mul_f32 v[222:223], v[224:225], v[222:223] op_sel_hi:[0,1]
	v_pk_fma_f32 v[192:193], v[0:1], v[208:209], v[192:193]
	v_pk_fma_f32 v[194:195], v[2:3], v[210:211], v[194:195]
	v_pk_fma_f32 v[196:197], v[4:5], v[212:213], v[196:197]
	v_pk_fma_f32 v[198:199], v[6:7], v[214:215], v[198:199]
	v_pk_fma_f32 v[200:201], v[8:9], v[216:217], v[200:201]
	v_pk_fma_f32 v[202:203], v[10:11], v[218:219], v[202:203]
	v_pk_fma_f32 v[204:205], v[12:13], v[220:221], v[204:205]
	v_pk_fma_f32 v[206:207], v[14:15], v[222:223], v[206:207]
	s_mov_b64 s[20:21], s[0:1]
	global_store_dwordx4 v19, v[192:195], s[20:21] offset:0 nt
	global_store_dwordx4 v19, v[196:199], s[20:21] offset:1024 nt
	global_store_dwordx4 v19, v[200:203], s[20:21] offset:2048 nt
	global_store_dwordx4 v19, v[204:207], s[20:21] offset:3072 nt
	s_add_u32 s12, s12, 0x300000
	s_addc_u32 s13, s13, 0
	s_add_u32 s14, s14, 0x300000
	s_addc_u32 s15, s15, 0
	global_load_dwordx2 v[64:65], v18, s[12:13] offset:0 nt
	global_load_dwordx2 v[66:67], v18, s[12:13] offset:512 nt
	global_load_dwordx2 v[68:69], v18, s[12:13] offset:1024 nt
	global_load_dwordx2 v[70:71], v18, s[12:13] offset:1536 nt
	global_load_dwordx2 v[72:73], v18, s[14:15] offset:0 nt
	global_load_dwordx2 v[74:75], v18, s[14:15] offset:512 nt
	global_load_dwordx2 v[76:77], v18, s[14:15] offset:1024 nt
	global_load_dwordx2 v[78:79], v18, s[14:15] offset:1536 nt
	s_waitcnt vmcnt(44)
	v_lshlrev_b32_e32 v208, 16, v88
	v_and_b32_e32 v209, 0xffff0000, v88
	v_lshlrev_b32_e32 v210, 16, v89
	v_and_b32_e32 v211, 0xffff0000, v89
	v_lshlrev_b32_e32 v212, 16, v90
	v_and_b32_e32 v213, 0xffff0000, v90
	v_lshlrev_b32_e32 v214, 16, v91
	v_and_b32_e32 v215, 0xffff0000, v91
	v_lshlrev_b32_e32 v216, 16, v92
	v_and_b32_e32 v217, 0xffff0000, v92
	v_lshlrev_b32_e32 v218, 16, v93
	v_and_b32_e32 v219, 0xffff0000, v93
	v_lshlrev_b32_e32 v220, 16, v94
	v_and_b32_e32 v221, 0xffff0000, v94
	v_lshlrev_b32_e32 v222, 16, v95
	v_and_b32_e32 v223, 0xffff0000, v95
	v_pk_mul_f32 v[224:225], v[208:209], v[208:209]
	v_pk_fma_f32 v[224:225], v[210:211], v[210:211], v[224:225]
	v_pk_fma_f32 v[224:225], v[212:213], v[212:213], v[224:225]
	v_pk_fma_f32 v[224:225], v[214:215], v[214:215], v[224:225]
	v_pk_fma_f32 v[224:225], v[216:217], v[216:217], v[224:225]
	v_pk_fma_f32 v[224:225], v[218:219], v[218:219], v[224:225]
	v_pk_fma_f32 v[224:225], v[220:221], v[220:221], v[224:225]
	v_pk_fma_f32 v[224:225], v[222:223], v[222:223], v[224:225]
	v_add_f32_e32 v224, v224, v225
	v_lshlrev_b32_e32 v192, 16, v80
	v_and_b32_e32 v193, 0xffff0000, v80
	v_lshlrev_b32_e32 v194, 16, v81
	v_and_b32_e32 v195, 0xffff0000, v81
	v_add_f32_dpp v224, v224, v224 quad_perm:[1,0,3,2] row_mask:0xf bank_mask:0xf bound_ctrl:1
	v_lshlrev_b32_e32 v196, 16, v82
	v_and_b32_e32 v197, 0xffff0000, v82
	v_lshlrev_b32_e32 v198, 16, v83
	v_and_b32_e32 v199, 0xffff0000, v83
; __device__ __forceinline__ unsigned cvt_pk_bf16(float lo, float hi) { const f32x2_t v = {lo, hi}; const bf16x2_t b = __builtin_convertvector(v, bf16x2_t); return __builtin_bit_cast(unsigned, b); }
; __device__ __forceinline__ float lo_bf(unsigned x) { return __uint_as_float(x << 16); }
; __device__ __forceinline__ float hi_bf(unsigned x) { return __uint_as_float(x & 0xffff0000u); }
; __device__ __forceinline__ void rows_proc(PR P, const int mode, const int row, const int lane, float4 (&xv)[4], const float4 (&fo)[4], const float4 (&gp)[4], const float4 (&gn)[4]) {
;     bf16_t* XN = (bf16_t*)(P.ws + WS_XN);
;     if (mode != 0) {
;         float ss = 0.f;
; #pragma unroll
;         for (int q = 0; q < 4; ++q) ss += fo[q].x * fo[q].x + fo[q].y * fo[q].y + fo[q].z * fo[q].z + fo[q].w * fo[q].w;
;         ss = wave_sum(ss); const float r = rsqrtf(ss * (1.0f / 1024.0f) + 1e-6f) * (mode == 2 ? 1.0f : 0.5f);
; #pragma unroll
;         for (int q = 0; q < 4; ++q) {
;             xv[q].x += fo[q].x * r * gp[q].x; xv[q].y += fo[q].y * r * gp[q].y; xv[q].z += fo[q].z * r * gp[q].z; xv[q].w += fo[q].w * r * gp[q].w;
;             if (mode == 3) { const f32x4 t_ = {xv[q].x, xv[q].y, xv[q].z, xv[q].w}; __builtin_nontemporal_store(t_, (f32x4*)(P.out + (size_t)row * 1024 + (q * 64 + lane) * 4)); }
;             else { bf16_t* xo = (mode == 1 ? (bf16_t*)P.out : (bf16_t*)(P.ws + WS_FO + 34603008)) + (size_t)row * 1024; u32x2 t; t.x = pg8::cvt_pk_bf16(xv[q].x, xv[q].y); t.y = pg8::cvt_pk_bf16(xv[q].z, xv[q].w);
;                 __builtin_nontemporal_store(t, (u32x2*)(xo + (q * 64 + lane) * 4)); } }
;         if (mode == 3) return;
; __device__ __forceinline__ void rows_phase(PR P, const int mode, LAS float* ldsf, const int wv) {
;     ...
;         for (int row = gw; row < MP; row += nw) {
;             const int nrow = row + nw < MP ? row + nw : last;
;             rows_load(P, mode, nrow, lane, N);
;             float4 xv[4], fo[4];
; #pragma unroll
;             for (int q = 0; q < 4; ++q) {
;                 xv[q] = mode <= 1 ? R.xf[q] : make_float4(lo_bf(R.xb[q].x), hi_bf(R.xb[q].x), lo_bf(R.xb[q].y), hi_bf(R.xb[q].y));
;                 fo[q] = make_float4(lo_bf(R.fb[q].x), hi_bf(R.fb[q].x), lo_bf(R.fb[q].y), hi_bf(R.fb[q].y)); }
;             rows_proc(P, mode, row, lane, xv, fo, gp, gn);
;             R = N;
;         }
	v_add_f32_dpp v224, v224, v224 quad_perm:[2,3,0,1] row_mask:0xf bank_mask:0xf bound_ctrl:1
	v_lshlrev_b32_e32 v200, 16, v84
	v_and_b32_e32 v201, 0xffff0000, v84
	v_lshlrev_b32_e32 v202, 16, v85
	v_and_b32_e32 v203, 0xffff0000, v85
	v_add_f32_dpp v224, v224, v224 row_half_mirror row_mask:0xf bank_mask:0xf bound_ctrl:1
	v_lshlrev_b32_e32 v204, 16, v86
	v_and_b32_e32 v205, 0xffff0000, v86
	v_lshlrev_b32_e32 v206, 16, v87
	v_and_b32_e32 v207, 0xffff0000, v87
	v_add_f32_dpp v224, v224, v224 row_mirror row_mask:0xf bank_mask:0xf bound_ctrl:1
	s_nop 0
	v_readlane_b32 s16, v224, 0
	v_readlane_b32 s17, v224, 16
	v_readlane_b32 s18, v224, 32
	v_readlane_b32 s19, v224, 48
	s_nop 1
	v_mov_b32_e32 v224, s17
	v_add_f32_e32 v224, s16, v224
	v_add_f32_e32 v224, s18, v224
	v_add_f32_e32 v224, s19, v224
	v_fmamk_f32 v224, v224, 0x3a800000, v226
	v_rsq_f32_e32 v224, v224
	s_nop 0
	v_mul_f32_e32 v224, 0.5, v224
	v_pk_mul_f32 v[208:209], v[224:225], v[208:209] op_sel_hi:[0,1]
	v_pk_mul_f32 v[210:211], v[224:225], v[210:211] op_sel_hi:[0,1]
	v_pk_mul_f32 v[212:213], v[224:225], v[212:213] op_sel_hi:[0,1]
	v_pk_mul_f32 v[214:215], v[224:225], v[214:215] op_sel_hi:[0,1]
	v_pk_mul_f32 v[216:217], v[224:225], v[216:217] op_sel_hi:[0,1]
	v_pk_mul_f32 v[218:219], v[224:225], v[218:219] op_sel_hi:[0,1]
	v_pk_mul_f32 v[220:221], v[224:225], v[220:221] op_sel_hi:[0,1]
	v_pk_mul_f32 v[222:223], v[224:225], v[222:223] op_sel_hi:[0,1]
	v_pk_fma_f32 v[192:193], v[0:1], v[208:209], v[192:193]
	v_pk_fma_f32 v[194:195], v[2:3], v[210:211], v[194:195]
	v_pk_fma_f32 v[196:197], v[4:5], v[212:213], v[196:197]
	v_pk_fma_f32 v[198:199], v[6:7], v[214:215], v[198:199]
	v_pk_fma_f32 v[200:201], v[8:9], v[216:217], v[200:201]
	v_pk_fma_f32 v[202:203], v[10:11], v[218:219], v[202:203]
	v_pk_fma_f32 v[204:205], v[12:13], v[220:221], v[204:205]
	v_pk_fma_f32 v[206:207], v[14:15], v[222:223], v[206:207]
	s_add_u32 s20, s20, 0x600000
	s_addc_u32 s21, s21, 0
	global_store_dwordx4 v19, v[192:195], s[20:21] offset:0 nt
	global_store_dwordx4 v19, v[196:199], s[20:21] offset:1024 nt
	global_store_dwordx4 v19, v[200:203], s[20:21] offset:2048 nt
	global_store_dwordx4 v19, v[204:207], s[20:21] offset:3072 nt
	s_add_u32 s12, s12, 0x300000
	s_addc_u32 s13, s13, 0
	s_add_u32 s14, s14, 0x300000
	s_addc_u32 s15, s15, 0
	global_load_dwordx2 v[80:81], v18, s[12:13] offset:0 nt
	global_load_dwordx2 v[82:83], v18, s[12:13] offset:512 nt
	global_load_dwordx2 v[84:85], v18, s[12:13] offset:1024 nt
	global_load_dwordx2 v[86:87], v18, s[12:13] offset:1536 nt
	global_load_dwordx2 v[88:89], v18, s[14:15] offset:0 nt
	global_load_dwordx2 v[90:91], v18, s[14:15] offset:512 nt
	global_load_dwordx2 v[92:93], v18, s[14:15] offset:1024 nt
	global_load_dwordx2 v[94:95], v18, s[14:15] offset:1536 nt
	s_waitcnt vmcnt(48)
	v_lshlrev_b32_e32 v208, 16, v104
	v_and_b32_e32 v209, 0xffff0000, v104
	v_lshlrev_b32_e32 v210, 16, v105
	v_and_b32_e32 v211, 0xffff0000, v105
	v_lshlrev_b32_e32 v212, 16, v106
	v_and_b32_e32 v213, 0xffff0000, v106
	v_lshlrev_b32_e32 v214, 16, v107
	v_and_b32_e32 v215, 0xffff0000, v107
	v_lshlrev_b32_e32 v216, 16, v108
	v_and_b32_e32 v217, 0xffff0000, v108
	v_lshlrev_b32_e32 v218, 16, v109
	v_and_b32_e32 v219, 0xffff0000, v109
	v_lshlrev_b32_e32 v220, 16, v110
	v_and_b32_e32 v221, 0xffff0000, v110
	v_lshlrev_b32_e32 v222, 16, v111
	v_and_b32_e32 v223, 0xffff0000, v111
	v_pk_mul_f32 v[224:225], v[208:209], v[208:209]
	v_pk_fma_f32 v[224:225], v[210:211], v[210:211], v[224:225]
	v_pk_fma_f32 v[224:225], v[212:213], v[212:213], v[224:225]
	v_pk_fma_f32 v[224:225], v[214:215], v[214:215], v[224:225]
	v_pk_fma_f32 v[224:225], v[216:217], v[216:217], v[224:225]
	v_pk_fma_f32 v[224:225], v[218:219], v[218:219], v[224:225]
	v_pk_fma_f32 v[224:225], v[220:221], v[220:221], v[224:225]
	v_pk_fma_f32 v[224:225], v[222:223], v[222:223], v[224:225]
	v_add_f32_e32 v224, v224, v225
	v_lshlrev_b32_e32 v192, 16, v96
	v_and_b32_e32 v193, 0xffff0000, v96
	v_lshlrev_b32_e32 v194, 16, v97
	v_and_b32_e32 v195, 0xffff0000, v97
	v_add_f32_dpp v224, v224, v224 quad_perm:[1,0,3,2] row_mask:0xf bank_mask:0xf bound_ctrl:1
	v_lshlrev_b32_e32 v196, 16, v98
	v_and_b32_e32 v197, 0xffff0000, v98
	v_lshlrev_b32_e32 v198, 16, v99
	v_and_b32_e32 v199, 0xffff0000, v99
	v_add_f32_dpp v224, v224, v224 quad_perm:[2,3,0,1] row_mask:0xf bank_mask:0xf bound_ctrl:1
	v_lshlrev_b32_e32 v200, 16, v100
	v_and_b32_e32 v201, 0xffff0000, v100
	v_lshlrev_b32_e32 v202, 16, v101
	v_and_b32_e32 v203, 0xffff0000, v101
	v_add_f32_dpp v224, v224, v224 row_half_mirror row_mask:0xf bank_mask:0xf bound_ctrl:1
	v_lshlrev_b32_e32 v204, 16, v102
	v_and_b32_e32 v205, 0xffff0000, v102
	v_lshlrev_b32_e32 v206, 16, v103
	v_and_b32_e32 v207, 0xffff0000, v103
	v_add_f32_dpp v224, v224, v224 row_mirror row_mask:0xf bank_mask:0xf bound_ctrl:1
	s_nop 0
	v_readlane_b32 s16, v224, 0
	v_readlane_b32 s17, v224, 16
	v_readlane_b32 s18, v224, 32
	v_readlane_b32 s19, v224, 48
	s_nop 1
	v_mov_b32_e32 v224, s17
	v_add_f32_e32 v224, s16, v224
	v_add_f32_e32 v224, s18, v224
	v_add_f32_e32 v224, s19, v224
	v_fmamk_f32 v224, v224, 0x3a800000, v226
	v_rsq_f32_e32 v224, v224
	s_nop 0
	v_mul_f32_e32 v224, 0.5, v224
	v_pk_mul_f32 v[208:209], v[224:225], v[208:209] op_sel_hi:[0,1]
	v_pk_mul_f32 v[210:211], v[224:225], v[210:211] op_sel_hi:[0,1]
	v_pk_mul_f32 v[212:213], v[224:225], v[212:213] op_sel_hi:[0,1]
	v_pk_mul_f32 v[214:215], v[224:225], v[214:215] op_sel_hi:[0,1]
	v_pk_mul_f32 v[216:217], v[224:225], v[216:217] op_sel_hi:[0,1]
	v_pk_mul_f32 v[218:219], v[224:225], v[218:219] op_sel_hi:[0,1]
	v_pk_mul_f32 v[220:221], v[224:225], v[220:221] op_sel_hi:[0,1]
; __device__ __forceinline__ unsigned cvt_pk_bf16(float lo, float hi) { const f32x2_t v = {lo, hi}; const bf16x2_t b = __builtin_convertvector(v, bf16x2_t); return __builtin_bit_cast(unsigned, b); }
; __device__ __forceinline__ float lo_bf(unsigned x) { return __uint_as_float(x << 16); }
; __device__ __forceinline__ float hi_bf(unsigned x) { return __uint_as_float(x & 0xffff0000u); }
; __device__ __forceinline__ void rows_proc(PR P, const int mode, const int row, const int lane, float4 (&xv)[4], const float4 (&fo)[4], const float4 (&gp)[4], const float4 (&gn)[4]) {
;     bf16_t* XN = (bf16_t*)(P.ws + WS_XN);
;     if (mode != 0) {
;         float ss = 0.f;
; #pragma unroll
;         for (int q = 0; q < 4; ++q) ss += fo[q].x * fo[q].x + fo[q].y * fo[q].y + fo[q].z * fo[q].z + fo[q].w * fo[q].w;
;         ss = wave_sum(ss); const float r = rsqrtf(ss * (1.0f / 1024.0f) + 1e-6f) * (mode == 2 ? 1.0f : 0.5f);
; #pragma unroll
;         for (int q = 0; q < 4; ++q) {
;             xv[q].x += fo[q].x * r * gp[q].x; xv[q].y += fo[q].y * r * gp[q].y; xv[q].z += fo[q].z * r * gp[q].z; xv[q].w += fo[q].w * r * gp[q].w;
;             if (mode == 3) { const f32x4 t_ = {xv[q].x, xv[q].y, xv[q].z, xv[q].w}; __builtin_nontemporal_store(t_, (f32x4*)(P.out + (size_t)row * 1024 + (q * 64 + lane) * 4)); }
;             else { bf16_t* xo = (mode == 1 ? (bf16_t*)P.out : (bf16_t*)(P.ws + WS_FO + 34603008)) + (size_t)row * 1024; u32x2 t; t.x = pg8::cvt_pk_bf16(xv[q].x, xv[q].y); t.y = pg8::cvt_pk_bf16(xv[q].z, xv[q].w);
;                 __builtin_nontemporal_store(t, (u32x2*)(xo + (q * 64 + lane) * 4)); } }
;         if (mode == 3) return;
; __device__ __forceinline__ void rows_phase(PR P, const int mode, LAS float* ldsf, const int wv) {
;     ...
;         for (int row = gw; row < MP; row += nw) {
;             const int nrow = row + nw < MP ? row + nw : last;
;             rows_load(P, mode, nrow, lane, N);
;             float4 xv[4], fo[4];
; #pragma unroll
;             for (int q = 0; q < 4; ++q) {
;                 xv[q] = mode <= 1 ? R.xf[q] : make_float4(lo_bf(R.xb[q].x), hi_bf(R.xb[q].x), lo_bf(R.xb[q].y), hi_bf(R.xb[q].y));
;                 fo[q] = make_float4(lo_bf(R.fb[q].x), hi_bf(R.fb[q].x), lo_bf(R.fb[q].y), hi_bf(R.fb[q].y)); }
;             rows_proc(P, mode, row, lane, xv, fo, gp, gn);
;             R = N;
;         }
	v_pk_mul_f32 v[222:223], v[224:225], v[222:223] op_sel_hi:[0,1]
	v_pk_fma_f32 v[192:193], v[0:1], v[208:209], v[192:193]
	v_pk_fma_f32 v[194:195], v[2:3], v[210:211], v[194:195]
	v_pk_fma_f32 v[196:197], v[4:5], v[212:213], v[196:197]
	v_pk_fma_f32 v[198:199], v[6:7], v[214:215], v[198:199]
	v_pk_fma_f32 v[200:201], v[8:9], v[216:217], v[200:201]
	v_pk_fma_f32 v[202:203], v[10:11], v[218:219], v[202:203]
	v_pk_fma_f32 v[204:205], v[12:13], v[220:221], v[204:205]
	v_pk_fma_f32 v[206:207], v[14:15], v[222:223], v[206:207]
	s_add_u32 s20, s20, 0x600000
	s_addc_u32 s21, s21, 0
	global_store_dwordx4 v19, v[192:195], s[20:21] offset:0 nt
	global_store_dwordx4 v19, v[196:199], s[20:21] offset:1024 nt
	global_store_dwordx4 v19, v[200:203], s[20:21] offset:2048 nt
	global_store_dwordx4 v19, v[204:207], s[20:21] offset:3072 nt
	s_add_u32 s12, s12, 0x300000
	s_addc_u32 s13, s13, 0
	s_add_u32 s14, s14, 0x300000
	s_addc_u32 s15, s15, 0
	global_load_dwordx2 v[96:97], v18, s[12:13] offset:0 nt
	global_load_dwordx2 v[98:99], v18, s[12:13] offset:512 nt
	global_load_dwordx2 v[100:101], v18, s[12:13] offset:1024 nt
	global_load_dwordx2 v[102:103], v18, s[12:13] offset:1536 nt
	global_load_dwordx2 v[104:105], v18, s[14:15] offset:0 nt
	global_load_dwordx2 v[106:107], v18, s[14:15] offset:512 nt
	global_load_dwordx2 v[108:109], v18, s[14:15] offset:1024 nt
	global_load_dwordx2 v[110:111], v18, s[14:15] offset:1536 nt
	s_waitcnt vmcnt(52)
	v_lshlrev_b32_e32 v208, 16, v120
	v_and_b32_e32 v209, 0xffff0000, v120
	v_lshlrev_b32_e32 v210, 16, v121
	v_and_b32_e32 v211, 0xffff0000, v121
	v_lshlrev_b32_e32 v212, 16, v122
	v_and_b32_e32 v213, 0xffff0000, v122
	v_lshlrev_b32_e32 v214, 16, v123
	v_and_b32_e32 v215, 0xffff0000, v123
	v_lshlrev_b32_e32 v216, 16, v124
	v_and_b32_e32 v217, 0xffff0000, v124
	v_lshlrev_b32_e32 v218, 16, v125
	v_and_b32_e32 v219, 0xffff0000, v125
	v_lshlrev_b32_e32 v220, 16, v126
	v_and_b32_e32 v221, 0xffff0000, v126
	v_lshlrev_b32_e32 v222, 16, v127
	v_and_b32_e32 v223, 0xffff0000, v127
	v_pk_mul_f32 v[224:225], v[208:209], v[208:209]
	v_pk_fma_f32 v[224:225], v[210:211], v[210:211], v[224:225]
	v_pk_fma_f32 v[224:225], v[212:213], v[212:213], v[224:225]
	v_pk_fma_f32 v[224:225], v[214:215], v[214:215], v[224:225]
	v_pk_fma_f32 v[224:225], v[216:217], v[216:217], v[224:225]
	v_pk_fma_f32 v[224:225], v[218:219], v[218:219], v[224:225]
	v_pk_fma_f32 v[224:225], v[220:221], v[220:221], v[224:225]
	v_pk_fma_f32 v[224:225], v[222:223], v[222:223], v[224:225]
	v_add_f32_e32 v224, v224, v225
	v_lshlrev_b32_e32 v192, 16, v112
	v_and_b32_e32 v193, 0xffff0000, v112
	v_lshlrev_b32_e32 v194, 16, v113
	v_and_b32_e32 v195, 0xffff0000, v113
	v_add_f32_dpp v224, v224, v224 quad_perm:[1,0,3,2] row_mask:0xf bank_mask:0xf bound_ctrl:1
	v_lshlrev_b32_e32 v196, 16, v114
	v_and_b32_e32 v197, 0xffff0000, v114
	v_lshlrev_b32_e32 v198, 16, v115
	v_and_b32_e32 v199, 0xffff0000, v115
	v_add_f32_dpp v224, v224, v224 quad_perm:[2,3,0,1] row_mask:0xf bank_mask:0xf bound_ctrl:1
	v_lshlrev_b32_e32 v200, 16, v116
	v_and_b32_e32 v201, 0xffff0000, v116
	v_lshlrev_b32_e32 v202, 16, v117
	v_and_b32_e32 v203, 0xffff0000, v117
	v_add_f32_dpp v224, v224, v224 row_half_mirror row_mask:0xf bank_mask:0xf bound_ctrl:1
	v_lshlrev_b32_e32 v204, 16, v118
	v_and_b32_e32 v205, 0xffff0000, v118
	v_lshlrev_b32_e32 v206, 16, v119
	v_and_b32_e32 v207, 0xffff0000, v119
	v_add_f32_dpp v224, v224, v224 row_mirror row_mask:0xf bank_mask:0xf bound_ctrl:1
	s_nop 0
	v_readlane_b32 s16, v224, 0
	v_readlane_b32 s17, v224, 16
	v_readlane_b32 s18, v224, 32
	v_readlane_b32 s19, v224, 48
	s_nop 1
	v_mov_b32_e32 v224, s17
	v_add_f32_e32 v224, s16, v224
	v_add_f32_e32 v224, s18, v224
	v_add_f32_e32 v224, s19, v224
	v_fmamk_f32 v224, v224, 0x3a800000, v226
	v_rsq_f32_e32 v224, v224
	s_nop 0
	v_mul_f32_e32 v224, 0.5, v224
	v_pk_mul_f32 v[208:209], v[224:225], v[208:209] op_sel_hi:[0,1]
	v_pk_mul_f32 v[210:211], v[224:225], v[210:211] op_sel_hi:[0,1]
	v_pk_mul_f32 v[212:213], v[224:225], v[212:213] op_sel_hi:[0,1]
	v_pk_mul_f32 v[214:215], v[224:225], v[214:215] op_sel_hi:[0,1]
	v_pk_mul_f32 v[216:217], v[224:225], v[216:217] op_sel_hi:[0,1]
	v_pk_mul_f32 v[218:219], v[224:225], v[218:219] op_sel_hi:[0,1]
	v_pk_mul_f32 v[220:221], v[224:225], v[220:221] op_sel_hi:[0,1]
	v_pk_mul_f32 v[222:223], v[224:225], v[222:223] op_sel_hi:[0,1]
	v_pk_fma_f32 v[192:193], v[0:1], v[208:209], v[192:193]
	v_pk_fma_f32 v[194:195], v[2:3], v[210:211], v[194:195]
	v_pk_fma_f32 v[196:197], v[4:5], v[212:213], v[196:197]
	v_pk_fma_f32 v[198:199], v[6:7], v[214:215], v[198:199]
	v_pk_fma_f32 v[200:201], v[8:9], v[216:217], v[200:201]
	v_pk_fma_f32 v[202:203], v[10:11], v[218:219], v[202:203]
	v_pk_fma_f32 v[204:205], v[12:13], v[220:221], v[204:205]
	v_pk_fma_f32 v[206:207], v[14:15], v[222:223], v[206:207]
	s_add_u32 s20, s20, 0x600000
	s_addc_u32 s21, s21, 0
	global_store_dwordx4 v19, v[192:195], s[20:21] offset:0 nt
	global_store_dwordx4 v19, v[196:199], s[20:21] offset:1024 nt
	global_store_dwordx4 v19, v[200:203], s[20:21] offset:2048 nt
	global_store_dwordx4 v19, v[204:207], s[20:21] offset:3072 nt
	s_waitcnt vmcnt(52)
	s_add_u32 s12, s12, 0x300000
	s_addc_u32 s13, s13, 0
	s_add_u32 s14, s14, 0x300000
	s_addc_u32 s15, s15, 0
	global_load_dwordx2 v[112:113], v18, s[12:13] offset:0 nt
	global_load_dwordx2 v[114:115], v18, s[12:13] offset:512 nt
	global_load_dwordx2 v[116:117], v18, s[12:13] offset:1024 nt
	global_load_dwordx2 v[118:119], v18, s[12:13] offset:1536 nt
	global_load_dwordx2 v[120:121], v18, s[14:15] offset:0 nt
	global_load_dwordx2 v[122:123], v18, s[14:15] offset:512 nt
	global_load_dwordx2 v[124:125], v18, s[14:15] offset:1024 nt
	global_load_dwordx2 v[126:127], v18, s[14:15] offset:1536 nt
	s_waitcnt vmcnt(56)
; __device__ __forceinline__ unsigned cvt_pk_bf16(float lo, float hi) { const f32x2_t v = {lo, hi}; const bf16x2_t b = __builtin_convertvector(v, bf16x2_t); return __builtin_bit_cast(unsigned, b); }
; __device__ __forceinline__ float lo_bf(unsigned x) { return __uint_as_float(x << 16); }
; __device__ __forceinline__ float hi_bf(unsigned x) { return __uint_as_float(x & 0xffff0000u); }
; __device__ __forceinline__ void rows_proc(PR P, const int mode, const int row, const int lane, float4 (&xv)[4], const float4 (&fo)[4], const float4 (&gp)[4], const float4 (&gn)[4]) {
;     bf16_t* XN = (bf16_t*)(P.ws + WS_XN);
;     if (mode != 0) {
;         float ss = 0.f;
; #pragma unroll
;         for (int q = 0; q < 4; ++q) ss += fo[q].x * fo[q].x + fo[q].y * fo[q].y + fo[q].z * fo[q].z + fo[q].w * fo[q].w;
;         ss = wave_sum(ss); const float r = rsqrtf(ss * (1.0f / 1024.0f) + 1e-6f) * (mode == 2 ? 1.0f : 0.5f);
; #pragma unroll
;         for (int q = 0; q < 4; ++q) {
;             xv[q].x += fo[q].x * r * gp[q].x; xv[q].y += fo[q].y * r * gp[q].y; xv[q].z += fo[q].z * r * gp[q].z; xv[q].w += fo[q].w * r * gp[q].w;
;             if (mode == 3) { const f32x4 t_ = {xv[q].x, xv[q].y, xv[q].z, xv[q].w}; __builtin_nontemporal_store(t_, (f32x4*)(P.out + (size_t)row * 1024 + (q * 64 + lane) * 4)); }
;             else { bf16_t* xo = (mode == 1 ? (bf16_t*)P.out : (bf16_t*)(P.ws + WS_FO + 34603008)) + (size_t)row * 1024; u32x2 t; t.x = pg8::cvt_pk_bf16(xv[q].x, xv[q].y); t.y = pg8::cvt_pk_bf16(xv[q].z, xv[q].w);
;                 __builtin_nontemporal_store(t, (u32x2*)(xo + (q * 64 + lane) * 4)); } }
;         if (mode == 3) return;
; __device__ __forceinline__ void rows_phase(PR P, const int mode, LAS float* ldsf, const int wv) {
;     ...
;         for (int row = gw; row < MP; row += nw) {
;             const int nrow = row + nw < MP ? row + nw : last;
;             rows_load(P, mode, nrow, lane, N);
;             float4 xv[4], fo[4];
; #pragma unroll
;             for (int q = 0; q < 4; ++q) {
;                 xv[q] = mode <= 1 ? R.xf[q] : make_float4(lo_bf(R.xb[q].x), hi_bf(R.xb[q].x), lo_bf(R.xb[q].y), hi_bf(R.xb[q].y));
;                 fo[q] = make_float4(lo_bf(R.fb[q].x), hi_bf(R.fb[q].x), lo_bf(R.fb[q].y), hi_bf(R.fb[q].y)); }
;             rows_proc(P, mode, row, lane, xv, fo, gp, gn);
;             R = N;
;         }
	v_lshlrev_b32_e32 v208, 16, v136
	v_and_b32_e32 v209, 0xffff0000, v136
	v_lshlrev_b32_e32 v210, 16, v137
	v_and_b32_e32 v211, 0xffff0000, v137
	v_lshlrev_b32_e32 v212, 16, v138
	v_and_b32_e32 v213, 0xffff0000, v138
	v_lshlrev_b32_e32 v214, 16, v139
	v_and_b32_e32 v215, 0xffff0000, v139
	v_lshlrev_b32_e32 v216, 16, v140
	v_and_b32_e32 v217, 0xffff0000, v140
	v_lshlrev_b32_e32 v218, 16, v141
	v_and_b32_e32 v219, 0xffff0000, v141
	v_lshlrev_b32_e32 v220, 16, v142
	v_and_b32_e32 v221, 0xffff0000, v142
	v_lshlrev_b32_e32 v222, 16, v143
	v_and_b32_e32 v223, 0xffff0000, v143
	v_pk_mul_f32 v[224:225], v[208:209], v[208:209]
	v_pk_fma_f32 v[224:225], v[210:211], v[210:211], v[224:225]
	v_pk_fma_f32 v[224:225], v[212:213], v[212:213], v[224:225]
	v_pk_fma_f32 v[224:225], v[214:215], v[214:215], v[224:225]
	v_pk_fma_f32 v[224:225], v[216:217], v[216:217], v[224:225]
	v_pk_fma_f32 v[224:225], v[218:219], v[218:219], v[224:225]
	v_pk_fma_f32 v[224:225], v[220:221], v[220:221], v[224:225]
	v_pk_fma_f32 v[224:225], v[222:223], v[222:223], v[224:225]
	v_add_f32_e32 v224, v224, v225
	v_lshlrev_b32_e32 v192, 16, v128
	v_and_b32_e32 v193, 0xffff0000, v128
	v_lshlrev_b32_e32 v194, 16, v129
	v_and_b32_e32 v195, 0xffff0000, v129
	v_add_f32_dpp v224, v224, v224 quad_perm:[1,0,3,2] row_mask:0xf bank_mask:0xf bound_ctrl:1
	v_lshlrev_b32_e32 v196, 16, v130
	v_and_b32_e32 v197, 0xffff0000, v130
	v_lshlrev_b32_e32 v198, 16, v131
	v_and_b32_e32 v199, 0xffff0000, v131
	v_add_f32_dpp v224, v224, v224 quad_perm:[2,3,0,1] row_mask:0xf bank_mask:0xf bound_ctrl:1
	v_lshlrev_b32_e32 v200, 16, v132
	v_and_b32_e32 v201, 0xffff0000, v132
	v_lshlrev_b32_e32 v202, 16, v133
	v_and_b32_e32 v203, 0xffff0000, v133
	v_add_f32_dpp v224, v224, v224 row_half_mirror row_mask:0xf bank_mask:0xf bound_ctrl:1
	v_lshlrev_b32_e32 v204, 16, v134
	v_and_b32_e32 v205, 0xffff0000, v134
	v_lshlrev_b32_e32 v206, 16, v135
	v_and_b32_e32 v207, 0xffff0000, v135
	v_add_f32_dpp v224, v224, v224 row_mirror row_mask:0xf bank_mask:0xf bound_ctrl:1
	s_nop 0
	v_readlane_b32 s16, v224, 0
	v_readlane_b32 s17, v224, 16
	v_readlane_b32 s18, v224, 32
	v_readlane_b32 s19, v224, 48
	s_nop 1
	v_mov_b32_e32 v224, s17
	v_add_f32_e32 v224, s16, v224
	v_add_f32_e32 v224, s18, v224
	v_add_f32_e32 v224, s19, v224
	v_fmamk_f32 v224, v224, 0x3a800000, v226
	v_rsq_f32_e32 v224, v224
	s_nop 0
	v_mul_f32_e32 v224, 0.5, v224
	v_pk_mul_f32 v[208:209], v[224:225], v[208:209] op_sel_hi:[0,1]
	v_pk_mul_f32 v[210:211], v[224:225], v[210:211] op_sel_hi:[0,1]
	v_pk_mul_f32 v[212:213], v[224:225], v[212:213] op_sel_hi:[0,1]
	v_pk_mul_f32 v[214:215], v[224:225], v[214:215] op_sel_hi:[0,1]
	v_pk_mul_f32 v[216:217], v[224:225], v[216:217] op_sel_hi:[0,1]
	v_pk_mul_f32 v[218:219], v[224:225], v[218:219] op_sel_hi:[0,1]
	v_pk_mul_f32 v[220:221], v[224:225], v[220:221] op_sel_hi:[0,1]
	v_pk_mul_f32 v[222:223], v[224:225], v[222:223] op_sel_hi:[0,1]
	v_pk_fma_f32 v[192:193], v[0:1], v[208:209], v[192:193]
	v_pk_fma_f32 v[194:195], v[2:3], v[210:211], v[194:195]
	v_pk_fma_f32 v[196:197], v[4:5], v[212:213], v[196:197]
	v_pk_fma_f32 v[198:199], v[6:7], v[214:215], v[198:199]
	v_pk_fma_f32 v[200:201], v[8:9], v[216:217], v[200:201]
	v_pk_fma_f32 v[202:203], v[10:11], v[218:219], v[202:203]
	v_pk_fma_f32 v[204:205], v[12:13], v[220:221], v[204:205]
	v_pk_fma_f32 v[206:207], v[14:15], v[222:223], v[206:207]
	s_add_u32 s20, s20, 0x600000
	s_addc_u32 s21, s21, 0
	global_store_dwordx4 v19, v[192:195], s[20:21] offset:0 nt
	global_store_dwordx4 v19, v[196:199], s[20:21] offset:1024 nt
	global_store_dwordx4 v19, v[200:203], s[20:21] offset:2048 nt
	global_store_dwordx4 v19, v[204:207], s[20:21] offset:3072 nt
	s_waitcnt vmcnt(52)
	v_lshlrev_b32_e32 v208, 16, v152
	v_and_b32_e32 v209, 0xffff0000, v152
	v_lshlrev_b32_e32 v210, 16, v153
	v_and_b32_e32 v211, 0xffff0000, v153
	v_lshlrev_b32_e32 v212, 16, v154
	v_and_b32_e32 v213, 0xffff0000, v154
	v_lshlrev_b32_e32 v214, 16, v155
	v_and_b32_e32 v215, 0xffff0000, v155
	v_lshlrev_b32_e32 v216, 16, v156
	v_and_b32_e32 v217, 0xffff0000, v156
	v_lshlrev_b32_e32 v218, 16, v157
	v_and_b32_e32 v219, 0xffff0000, v157
	v_lshlrev_b32_e32 v220, 16, v158
	v_and_b32_e32 v221, 0xffff0000, v158
	v_lshlrev_b32_e32 v222, 16, v159
	v_and_b32_e32 v223, 0xffff0000, v159
	v_pk_mul_f32 v[224:225], v[208:209], v[208:209]
	v_pk_fma_f32 v[224:225], v[210:211], v[210:211], v[224:225]
	v_pk_fma_f32 v[224:225], v[212:213], v[212:213], v[224:225]
	v_pk_fma_f32 v[224:225], v[214:215], v[214:215], v[224:225]
	v_pk_fma_f32 v[224:225], v[216:217], v[216:217], v[224:225]
	v_pk_fma_f32 v[224:225], v[218:219], v[218:219], v[224:225]
	v_pk_fma_f32 v[224:225], v[220:221], v[220:221], v[224:225]
	v_pk_fma_f32 v[224:225], v[222:223], v[222:223], v[224:225]
	v_add_f32_e32 v224, v224, v225
	v_lshlrev_b32_e32 v192, 16, v144
	v_and_b32_e32 v193, 0xffff0000, v144
	v_lshlrev_b32_e32 v194, 16, v145
	v_and_b32_e32 v195, 0xffff0000, v145
	v_add_f32_dpp v224, v224, v224 quad_perm:[1,0,3,2] row_mask:0xf bank_mask:0xf bound_ctrl:1
	v_lshlrev_b32_e32 v196, 16, v146
	v_and_b32_e32 v197, 0xffff0000, v146
	v_lshlrev_b32_e32 v198, 16, v147
	v_and_b32_e32 v199, 0xffff0000, v147
	v_add_f32_dpp v224, v224, v224 quad_perm:[2,3,0,1] row_mask:0xf bank_mask:0xf bound_ctrl:1
	v_lshlrev_b32_e32 v200, 16, v148
	v_and_b32_e32 v201, 0xffff0000, v148
	v_lshlrev_b32_e32 v202, 16, v149
	v_and_b32_e32 v203, 0xffff0000, v149
	v_add_f32_dpp v224, v224, v224 row_half_mirror row_mask:0xf bank_mask:0xf bound_ctrl:1
	v_lshlrev_b32_e32 v204, 16, v150
	v_and_b32_e32 v205, 0xffff0000, v150
	v_lshlrev_b32_e32 v206, 16, v151
	v_and_b32_e32 v207, 0xffff0000, v151
; __device__ __forceinline__ unsigned cvt_pk_bf16(float lo, float hi) { const f32x2_t v = {lo, hi}; const bf16x2_t b = __builtin_convertvector(v, bf16x2_t); return __builtin_bit_cast(unsigned, b); }
; __device__ __forceinline__ float lo_bf(unsigned x) { return __uint_as_float(x << 16); }
; __device__ __forceinline__ float hi_bf(unsigned x) { return __uint_as_float(x & 0xffff0000u); }
; __device__ __forceinline__ void rows_proc(PR P, const int mode, const int row, const int lane, float4 (&xv)[4], const float4 (&fo)[4], const float4 (&gp)[4], const float4 (&gn)[4]) {
;     bf16_t* XN = (bf16_t*)(P.ws + WS_XN);
;     if (mode != 0) {
;         float ss = 0.f;
; #pragma unroll
;         for (int q = 0; q < 4; ++q) ss += fo[q].x * fo[q].x + fo[q].y * fo[q].y + fo[q].z * fo[q].z + fo[q].w * fo[q].w;
;         ss = wave_sum(ss); const float r = rsqrtf(ss * (1.0f / 1024.0f) + 1e-6f) * (mode == 2 ? 1.0f : 0.5f);
; #pragma unroll
;         for (int q = 0; q < 4; ++q) {
;             xv[q].x += fo[q].x * r * gp[q].x; xv[q].y += fo[q].y * r * gp[q].y; xv[q].z += fo[q].z * r * gp[q].z; xv[q].w += fo[q].w * r * gp[q].w;
;             if (mode == 3) { const f32x4 t_ = {xv[q].x, xv[q].y, xv[q].z, xv[q].w}; __builtin_nontemporal_store(t_, (f32x4*)(P.out + (size_t)row * 1024 + (q * 64 + lane) * 4)); }
;             else { bf16_t* xo = (mode == 1 ? (bf16_t*)P.out : (bf16_t*)(P.ws + WS_FO + 34603008)) + (size_t)row * 1024; u32x2 t; t.x = pg8::cvt_pk_bf16(xv[q].x, xv[q].y); t.y = pg8::cvt_pk_bf16(xv[q].z, xv[q].w);
;                 __builtin_nontemporal_store(t, (u32x2*)(xo + (q * 64 + lane) * 4)); } }
;         if (mode == 3) return;
; __device__ __forceinline__ void rows_phase(PR P, const int mode, LAS float* ldsf, const int wv) {
;     ...
;         for (int row = gw; row < MP; row += nw) {
;             const int nrow = row + nw < MP ? row + nw : last;
;             rows_load(P, mode, nrow, lane, N);
;             float4 xv[4], fo[4];
; #pragma unroll
;             for (int q = 0; q < 4; ++q) {
;                 xv[q] = mode <= 1 ? R.xf[q] : make_float4(lo_bf(R.xb[q].x), hi_bf(R.xb[q].x), lo_bf(R.xb[q].y), hi_bf(R.xb[q].y));
;                 fo[q] = make_float4(lo_bf(R.fb[q].x), hi_bf(R.fb[q].x), lo_bf(R.fb[q].y), hi_bf(R.fb[q].y)); }
;             rows_proc(P, mode, row, lane, xv, fo, gp, gn);
;             R = N;
;         }
	v_add_f32_dpp v224, v224, v224 row_mirror row_mask:0xf bank_mask:0xf bound_ctrl:1
	s_nop 0
	v_readlane_b32 s16, v224, 0
	v_readlane_b32 s17, v224, 16
	v_readlane_b32 s18, v224, 32
	v_readlane_b32 s19, v224, 48
	s_nop 1
	v_mov_b32_e32 v224, s17
	v_add_f32_e32 v224, s16, v224
	v_add_f32_e32 v224, s18, v224
	v_add_f32_e32 v224, s19, v224
	v_fmamk_f32 v224, v224, 0x3a800000, v226
	v_rsq_f32_e32 v224, v224
	s_nop 0
	v_mul_f32_e32 v224, 0.5, v224
	v_pk_mul_f32 v[208:209], v[224:225], v[208:209] op_sel_hi:[0,1]
	v_pk_mul_f32 v[210:211], v[224:225], v[210:211] op_sel_hi:[0,1]
	v_pk_mul_f32 v[212:213], v[224:225], v[212:213] op_sel_hi:[0,1]
	v_pk_mul_f32 v[214:215], v[224:225], v[214:215] op_sel_hi:[0,1]
	v_pk_mul_f32 v[216:217], v[224:225], v[216:217] op_sel_hi:[0,1]
	v_pk_mul_f32 v[218:219], v[224:225], v[218:219] op_sel_hi:[0,1]
	v_pk_mul_f32 v[220:221], v[224:225], v[220:221] op_sel_hi:[0,1]
	v_pk_mul_f32 v[222:223], v[224:225], v[222:223] op_sel_hi:[0,1]
	v_pk_fma_f32 v[192:193], v[0:1], v[208:209], v[192:193]
	v_pk_fma_f32 v[194:195], v[2:3], v[210:211], v[194:195]
	v_pk_fma_f32 v[196:197], v[4:5], v[212:213], v[196:197]
	v_pk_fma_f32 v[198:199], v[6:7], v[214:215], v[198:199]
	v_pk_fma_f32 v[200:201], v[8:9], v[216:217], v[200:201]
	v_pk_fma_f32 v[202:203], v[10:11], v[218:219], v[202:203]
	v_pk_fma_f32 v[204:205], v[12:13], v[220:221], v[204:205]
	v_pk_fma_f32 v[206:207], v[14:15], v[222:223], v[206:207]
	s_add_u32 s20, s20, 0x600000
	s_addc_u32 s21, s21, 0
	global_store_dwordx4 v19, v[192:195], s[20:21] offset:0 nt
	global_store_dwordx4 v19, v[196:199], s[20:21] offset:1024 nt
	global_store_dwordx4 v19, v[200:203], s[20:21] offset:2048 nt
	global_store_dwordx4 v19, v[204:207], s[20:21] offset:3072 nt
	s_waitcnt vmcnt(44)
	v_lshlrev_b32_e32 v208, 16, v72
	v_and_b32_e32 v209, 0xffff0000, v72
	v_lshlrev_b32_e32 v210, 16, v73
	v_and_b32_e32 v211, 0xffff0000, v73
	v_lshlrev_b32_e32 v212, 16, v74
	v_and_b32_e32 v213, 0xffff0000, v74
	v_lshlrev_b32_e32 v214, 16, v75
	v_and_b32_e32 v215, 0xffff0000, v75
	v_lshlrev_b32_e32 v216, 16, v76
	v_and_b32_e32 v217, 0xffff0000, v76
	v_lshlrev_b32_e32 v218, 16, v77
	v_and_b32_e32 v219, 0xffff0000, v77
	v_lshlrev_b32_e32 v220, 16, v78
	v_and_b32_e32 v221, 0xffff0000, v78
	v_lshlrev_b32_e32 v222, 16, v79
	v_and_b32_e32 v223, 0xffff0000, v79
	v_pk_mul_f32 v[224:225], v[208:209], v[208:209]
	v_pk_fma_f32 v[224:225], v[210:211], v[210:211], v[224:225]
	v_pk_fma_f32 v[224:225], v[212:213], v[212:213], v[224:225]
	v_pk_fma_f32 v[224:225], v[214:215], v[214:215], v[224:225]
	v_pk_fma_f32 v[224:225], v[216:217], v[216:217], v[224:225]
	v_pk_fma_f32 v[224:225], v[218:219], v[218:219], v[224:225]
	v_pk_fma_f32 v[224:225], v[220:221], v[220:221], v[224:225]
	v_pk_fma_f32 v[224:225], v[222:223], v[222:223], v[224:225]
	v_add_f32_e32 v224, v224, v225
	v_lshlrev_b32_e32 v192, 16, v64
	v_and_b32_e32 v193, 0xffff0000, v64
	v_lshlrev_b32_e32 v194, 16, v65
	v_and_b32_e32 v195, 0xffff0000, v65
	v_add_f32_dpp v224, v224, v224 quad_perm:[1,0,3,2] row_mask:0xf bank_mask:0xf bound_ctrl:1
	v_lshlrev_b32_e32 v196, 16, v66
	v_and_b32_e32 v197, 0xffff0000, v66
	v_lshlrev_b32_e32 v198, 16, v67
	v_and_b32_e32 v199, 0xffff0000, v67
	v_add_f32_dpp v224, v224, v224 quad_perm:[2,3,0,1] row_mask:0xf bank_mask:0xf bound_ctrl:1
	v_lshlrev_b32_e32 v200, 16, v68
	v_and_b32_e32 v201, 0xffff0000, v68
	v_lshlrev_b32_e32 v202, 16, v69
	v_and_b32_e32 v203, 0xffff0000, v69
	v_add_f32_dpp v224, v224, v224 row_half_mirror row_mask:0xf bank_mask:0xf bound_ctrl:1
	v_lshlrev_b32_e32 v204, 16, v70
	v_and_b32_e32 v205, 0xffff0000, v70
	v_lshlrev_b32_e32 v206, 16, v71
	v_and_b32_e32 v207, 0xffff0000, v71
	v_add_f32_dpp v224, v224, v224 row_mirror row_mask:0xf bank_mask:0xf bound_ctrl:1
	s_nop 0
	v_readlane_b32 s16, v224, 0
	v_readlane_b32 s17, v224, 16
	v_readlane_b32 s18, v224, 32
	v_readlane_b32 s19, v224, 48
	s_nop 1
	v_mov_b32_e32 v224, s17
	v_add_f32_e32 v224, s16, v224
	v_add_f32_e32 v224, s18, v224
	v_add_f32_e32 v224, s19, v224
	v_fmamk_f32 v224, v224, 0x3a800000, v226
	v_rsq_f32_e32 v224, v224
	s_nop 0
	v_mul_f32_e32 v224, 0.5, v224
	v_pk_mul_f32 v[208:209], v[224:225], v[208:209] op_sel_hi:[0,1]
	v_pk_mul_f32 v[210:211], v[224:225], v[210:211] op_sel_hi:[0,1]
	v_pk_mul_f32 v[212:213], v[224:225], v[212:213] op_sel_hi:[0,1]
	v_pk_mul_f32 v[214:215], v[224:225], v[214:215] op_sel_hi:[0,1]
	v_pk_mul_f32 v[216:217], v[224:225], v[216:217] op_sel_hi:[0,1]
	v_pk_mul_f32 v[218:219], v[224:225], v[218:219] op_sel_hi:[0,1]
	v_pk_mul_f32 v[220:221], v[224:225], v[220:221] op_sel_hi:[0,1]
	v_pk_mul_f32 v[222:223], v[224:225], v[222:223] op_sel_hi:[0,1]
	v_pk_fma_f32 v[192:193], v[0:1], v[208:209], v[192:193]
	v_pk_fma_f32 v[194:195], v[2:3], v[210:211], v[194:195]
	v_pk_fma_f32 v[196:197], v[4:5], v[212:213], v[196:197]
	v_pk_fma_f32 v[198:199], v[6:7], v[214:215], v[198:199]
	v_pk_fma_f32 v[200:201], v[8:9], v[216:217], v[200:201]
	v_pk_fma_f32 v[202:203], v[10:11], v[218:219], v[202:203]
	v_pk_fma_f32 v[204:205], v[12:13], v[220:221], v[204:205]
	v_pk_fma_f32 v[206:207], v[14:15], v[222:223], v[206:207]
	s_add_u32 s20, s20, 0x600000
	s_addc_u32 s21, s21, 0
	global_store_dwordx4 v19, v[192:195], s[20:21] offset:0 nt
	global_store_dwordx4 v19, v[196:199], s[20:21] offset:1024 nt
	global_store_dwordx4 v19, v[200:203], s[20:21] offset:2048 nt
	global_store_dwordx4 v19, v[204:207], s[20:21] offset:3072 nt
	s_waitcnt vmcnt(36)
; __device__ __forceinline__ unsigned cvt_pk_bf16(float lo, float hi) { const f32x2_t v = {lo, hi}; const bf16x2_t b = __builtin_convertvector(v, bf16x2_t); return __builtin_bit_cast(unsigned, b); }
; __device__ __forceinline__ float lo_bf(unsigned x) { return __uint_as_float(x << 16); }
; __device__ __forceinline__ float hi_bf(unsigned x) { return __uint_as_float(x & 0xffff0000u); }
; __device__ __forceinline__ void rows_proc(PR P, const int mode, const int row, const int lane, float4 (&xv)[4], const float4 (&fo)[4], const float4 (&gp)[4], const float4 (&gn)[4]) {
;     bf16_t* XN = (bf16_t*)(P.ws + WS_XN);
;     if (mode != 0) {
;         float ss = 0.f;
; #pragma unroll
;         for (int q = 0; q < 4; ++q) ss += fo[q].x * fo[q].x + fo[q].y * fo[q].y + fo[q].z * fo[q].z + fo[q].w * fo[q].w;
;         ss = wave_sum(ss); const float r = rsqrtf(ss * (1.0f / 1024.0f) + 1e-6f) * (mode == 2 ? 1.0f : 0.5f);
; #pragma unroll
;         for (int q = 0; q < 4; ++q) {
;             xv[q].x += fo[q].x * r * gp[q].x; xv[q].y += fo[q].y * r * gp[q].y; xv[q].z += fo[q].z * r * gp[q].z; xv[q].w += fo[q].w * r * gp[q].w;
;             if (mode == 3) { const f32x4 t_ = {xv[q].x, xv[q].y, xv[q].z, xv[q].w}; __builtin_nontemporal_store(t_, (f32x4*)(P.out + (size_t)row * 1024 + (q * 64 + lane) * 4)); }
;             else { bf16_t* xo = (mode == 1 ? (bf16_t*)P.out : (bf16_t*)(P.ws + WS_FO + 34603008)) + (size_t)row * 1024; u32x2 t; t.x = pg8::cvt_pk_bf16(xv[q].x, xv[q].y); t.y = pg8::cvt_pk_bf16(xv[q].z, xv[q].w);
;                 __builtin_nontemporal_store(t, (u32x2*)(xo + (q * 64 + lane) * 4)); } }
;         if (mode == 3) return;
; __device__ __forceinline__ void rows_phase(PR P, const int mode, LAS float* ldsf, const int wv) {
;     ...
;         for (int row = gw; row < MP; row += nw) {
;             const int nrow = row + nw < MP ? row + nw : last;
;             rows_load(P, mode, nrow, lane, N);
;             float4 xv[4], fo[4];
; #pragma unroll
;             for (int q = 0; q < 4; ++q) {
;                 xv[q] = mode <= 1 ? R.xf[q] : make_float4(lo_bf(R.xb[q].x), hi_bf(R.xb[q].x), lo_bf(R.xb[q].y), hi_bf(R.xb[q].y));
;                 fo[q] = make_float4(lo_bf(R.fb[q].x), hi_bf(R.fb[q].x), lo_bf(R.fb[q].y), hi_bf(R.fb[q].y)); }
;             rows_proc(P, mode, row, lane, xv, fo, gp, gn);
;             R = N;
;         }
	v_lshlrev_b32_e32 v208, 16, v88
	v_and_b32_e32 v209, 0xffff0000, v88
	v_lshlrev_b32_e32 v210, 16, v89
	v_and_b32_e32 v211, 0xffff0000, v89
	v_lshlrev_b32_e32 v212, 16, v90
	v_and_b32_e32 v213, 0xffff0000, v90
	v_lshlrev_b32_e32 v214, 16, v91
	v_and_b32_e32 v215, 0xffff0000, v91
	v_lshlrev_b32_e32 v216, 16, v92
	v_and_b32_e32 v217, 0xffff0000, v92
	v_lshlrev_b32_e32 v218, 16, v93
	v_and_b32_e32 v219, 0xffff0000, v93
	v_lshlrev_b32_e32 v220, 16, v94
	v_and_b32_e32 v221, 0xffff0000, v94
	v_lshlrev_b32_e32 v222, 16, v95
	v_and_b32_e32 v223, 0xffff0000, v95
	v_pk_mul_f32 v[224:225], v[208:209], v[208:209]
	v_pk_fma_f32 v[224:225], v[210:211], v[210:211], v[224:225]
	v_pk_fma_f32 v[224:225], v[212:213], v[212:213], v[224:225]
	v_pk_fma_f32 v[224:225], v[214:215], v[214:215], v[224:225]
	v_pk_fma_f32 v[224:225], v[216:217], v[216:217], v[224:225]
	v_pk_fma_f32 v[224:225], v[218:219], v[218:219], v[224:225]
	v_pk_fma_f32 v[224:225], v[220:221], v[220:221], v[224:225]
	v_pk_fma_f32 v[224:225], v[222:223], v[222:223], v[224:225]
	v_add_f32_e32 v224, v224, v225
	v_lshlrev_b32_e32 v192, 16, v80
	v_and_b32_e32 v193, 0xffff0000, v80
	v_lshlrev_b32_e32 v194, 16, v81
	v_and_b32_e32 v195, 0xffff0000, v81
	v_add_f32_dpp v224, v224, v224 quad_perm:[1,0,3,2] row_mask:0xf bank_mask:0xf bound_ctrl:1
	v_lshlrev_b32_e32 v196, 16, v82
	v_and_b32_e32 v197, 0xffff0000, v82
	v_lshlrev_b32_e32 v198, 16, v83
	v_and_b32_e32 v199, 0xffff0000, v83
	v_add_f32_dpp v224, v224, v224 quad_perm:[2,3,0,1] row_mask:0xf bank_mask:0xf bound_ctrl:1
	v_lshlrev_b32_e32 v200, 16, v84
	v_and_b32_e32 v201, 0xffff0000, v84
	v_lshlrev_b32_e32 v202, 16, v85
	v_and_b32_e32 v203, 0xffff0000, v85
	v_add_f32_dpp v224, v224, v224 row_half_mirror row_mask:0xf bank_mask:0xf bound_ctrl:1
	v_lshlrev_b32_e32 v204, 16, v86
	v_and_b32_e32 v205, 0xffff0000, v86
	v_lshlrev_b32_e32 v206, 16, v87
	v_and_b32_e32 v207, 0xffff0000, v87
	v_add_f32_dpp v224, v224, v224 row_mirror row_mask:0xf bank_mask:0xf bound_ctrl:1
	s_nop 0
	v_readlane_b32 s16, v224, 0
	v_readlane_b32 s17, v224, 16
	v_readlane_b32 s18, v224, 32
	v_readlane_b32 s19, v224, 48
	s_nop 1
	v_mov_b32_e32 v224, s17
	v_add_f32_e32 v224, s16, v224
	v_add_f32_e32 v224, s18, v224
	v_add_f32_e32 v224, s19, v224
	v_fmamk_f32 v224, v224, 0x3a800000, v226
	v_rsq_f32_e32 v224, v224
	s_nop 0
	v_mul_f32_e32 v224, 0.5, v224
	v_pk_mul_f32 v[208:209], v[224:225], v[208:209] op_sel_hi:[0,1]
	v_pk_mul_f32 v[210:211], v[224:225], v[210:211] op_sel_hi:[0,1]
	v_pk_mul_f32 v[212:213], v[224:225], v[212:213] op_sel_hi:[0,1]
	v_pk_mul_f32 v[214:215], v[224:225], v[214:215] op_sel_hi:[0,1]
	v_pk_mul_f32 v[216:217], v[224:225], v[216:217] op_sel_hi:[0,1]
	v_pk_mul_f32 v[218:219], v[224:225], v[218:219] op_sel_hi:[0,1]
	v_pk_mul_f32 v[220:221], v[224:225], v[220:221] op_sel_hi:[0,1]
	v_pk_mul_f32 v[222:223], v[224:225], v[222:223] op_sel_hi:[0,1]
	v_pk_fma_f32 v[192:193], v[0:1], v[208:209], v[192:193]
	v_pk_fma_f32 v[194:195], v[2:3], v[210:211], v[194:195]
	v_pk_fma_f32 v[196:197], v[4:5], v[212:213], v[196:197]
	v_pk_fma_f32 v[198:199], v[6:7], v[214:215], v[198:199]
	v_pk_fma_f32 v[200:201], v[8:9], v[216:217], v[200:201]
	v_pk_fma_f32 v[202:203], v[10:11], v[218:219], v[202:203]
	v_pk_fma_f32 v[204:205], v[12:13], v[220:221], v[204:205]
	v_pk_fma_f32 v[206:207], v[14:15], v[222:223], v[206:207]
	s_add_u32 s20, s20, 0x600000
	s_addc_u32 s21, s21, 0
	global_store_dwordx4 v19, v[192:195], s[20:21] offset:0 nt
	global_store_dwordx4 v19, v[196:199], s[20:21] offset:1024 nt
	global_store_dwordx4 v19, v[200:203], s[20:21] offset:2048 nt
	global_store_dwordx4 v19, v[204:207], s[20:21] offset:3072 nt
	s_waitcnt vmcnt(28)
	v_lshlrev_b32_e32 v208, 16, v104
	v_and_b32_e32 v209, 0xffff0000, v104
	v_lshlrev_b32_e32 v210, 16, v105
	v_and_b32_e32 v211, 0xffff0000, v105
	v_lshlrev_b32_e32 v212, 16, v106
	v_and_b32_e32 v213, 0xffff0000, v106
	v_lshlrev_b32_e32 v214, 16, v107
	v_and_b32_e32 v215, 0xffff0000, v107
	v_lshlrev_b32_e32 v216, 16, v108
	v_and_b32_e32 v217, 0xffff0000, v108
	v_lshlrev_b32_e32 v218, 16, v109
	v_and_b32_e32 v219, 0xffff0000, v109
	v_lshlrev_b32_e32 v220, 16, v110
	v_and_b32_e32 v221, 0xffff0000, v110
	v_lshlrev_b32_e32 v222, 16, v111
	v_and_b32_e32 v223, 0xffff0000, v111
	v_pk_mul_f32 v[224:225], v[208:209], v[208:209]
	v_pk_fma_f32 v[224:225], v[210:211], v[210:211], v[224:225]
	v_pk_fma_f32 v[224:225], v[212:213], v[212:213], v[224:225]
	v_pk_fma_f32 v[224:225], v[214:215], v[214:215], v[224:225]
	v_pk_fma_f32 v[224:225], v[216:217], v[216:217], v[224:225]
	v_pk_fma_f32 v[224:225], v[218:219], v[218:219], v[224:225]
	v_pk_fma_f32 v[224:225], v[220:221], v[220:221], v[224:225]
	v_pk_fma_f32 v[224:225], v[222:223], v[222:223], v[224:225]
	v_add_f32_e32 v224, v224, v225
	v_lshlrev_b32_e32 v192, 16, v96
	v_and_b32_e32 v193, 0xffff0000, v96
	v_lshlrev_b32_e32 v194, 16, v97
	v_and_b32_e32 v195, 0xffff0000, v97
	v_add_f32_dpp v224, v224, v224 quad_perm:[1,0,3,2] row_mask:0xf bank_mask:0xf bound_ctrl:1
	v_lshlrev_b32_e32 v196, 16, v98
	v_and_b32_e32 v197, 0xffff0000, v98
	v_lshlrev_b32_e32 v198, 16, v99
	v_and_b32_e32 v199, 0xffff0000, v99
	v_add_f32_dpp v224, v224, v224 quad_perm:[2,3,0,1] row_mask:0xf bank_mask:0xf bound_ctrl:1
	v_lshlrev_b32_e32 v200, 16, v100
	v_and_b32_e32 v201, 0xffff0000, v100
	v_lshlrev_b32_e32 v202, 16, v101
	v_and_b32_e32 v203, 0xffff0000, v101
	v_add_f32_dpp v224, v224, v224 row_half_mirror row_mask:0xf bank_mask:0xf bound_ctrl:1
	v_lshlrev_b32_e32 v204, 16, v102
	v_and_b32_e32 v205, 0xffff0000, v102
	v_lshlrev_b32_e32 v206, 16, v103
	v_and_b32_e32 v207, 0xffff0000, v103
	v_add_f32_dpp v224, v224, v224 row_mirror row_mask:0xf bank_mask:0xf bound_ctrl:1
; __device__ __forceinline__ unsigned cvt_pk_bf16(float lo, float hi) { const f32x2_t v = {lo, hi}; const bf16x2_t b = __builtin_convertvector(v, bf16x2_t); return __builtin_bit_cast(unsigned, b); }
; __device__ __forceinline__ float lo_bf(unsigned x) { return __uint_as_float(x << 16); }
; __device__ __forceinline__ float hi_bf(unsigned x) { return __uint_as_float(x & 0xffff0000u); }
; __device__ __forceinline__ void rows_proc(PR P, const int mode, const int row, const int lane, float4 (&xv)[4], const float4 (&fo)[4], const float4 (&gp)[4], const float4 (&gn)[4]) {
;     bf16_t* XN = (bf16_t*)(P.ws + WS_XN);
;     if (mode != 0) {
;         float ss = 0.f;
; #pragma unroll
;         for (int q = 0; q < 4; ++q) ss += fo[q].x * fo[q].x + fo[q].y * fo[q].y + fo[q].z * fo[q].z + fo[q].w * fo[q].w;
;         ss = wave_sum(ss); const float r = rsqrtf(ss * (1.0f / 1024.0f) + 1e-6f) * (mode == 2 ? 1.0f : 0.5f);
; #pragma unroll
;         for (int q = 0; q < 4; ++q) {
;             xv[q].x += fo[q].x * r * gp[q].x; xv[q].y += fo[q].y * r * gp[q].y; xv[q].z += fo[q].z * r * gp[q].z; xv[q].w += fo[q].w * r * gp[q].w;
;             if (mode == 3) { const f32x4 t_ = {xv[q].x, xv[q].y, xv[q].z, xv[q].w}; __builtin_nontemporal_store(t_, (f32x4*)(P.out + (size_t)row * 1024 + (q * 64 + lane) * 4)); }
;             else { bf16_t* xo = (mode == 1 ? (bf16_t*)P.out : (bf16_t*)(P.ws + WS_FO + 34603008)) + (size_t)row * 1024; u32x2 t; t.x = pg8::cvt_pk_bf16(xv[q].x, xv[q].y); t.y = pg8::cvt_pk_bf16(xv[q].z, xv[q].w);
;                 __builtin_nontemporal_store(t, (u32x2*)(xo + (q * 64 + lane) * 4)); } }
;         if (mode == 3) return;
; __device__ __forceinline__ void rows_phase(PR P, const int mode, LAS float* ldsf, const int wv) {
;     ...
;         for (int row = gw; row < MP; row += nw) {
;             const int nrow = row + nw < MP ? row + nw : last;
;             rows_load(P, mode, nrow, lane, N);
;             float4 xv[4], fo[4];
; #pragma unroll
;             for (int q = 0; q < 4; ++q) {
;                 xv[q] = mode <= 1 ? R.xf[q] : make_float4(lo_bf(R.xb[q].x), hi_bf(R.xb[q].x), lo_bf(R.xb[q].y), hi_bf(R.xb[q].y));
;                 fo[q] = make_float4(lo_bf(R.fb[q].x), hi_bf(R.fb[q].x), lo_bf(R.fb[q].y), hi_bf(R.fb[q].y)); }
;             rows_proc(P, mode, row, lane, xv, fo, gp, gn);
;             R = N;
;         }
	s_nop 0
	v_readlane_b32 s16, v224, 0
	v_readlane_b32 s17, v224, 16
	v_readlane_b32 s18, v224, 32
	v_readlane_b32 s19, v224, 48
	s_nop 1
	v_mov_b32_e32 v224, s17
	v_add_f32_e32 v224, s16, v224
	v_add_f32_e32 v224, s18, v224
	v_add_f32_e32 v224, s19, v224
	v_fmamk_f32 v224, v224, 0x3a800000, v226
	v_rsq_f32_e32 v224, v224
	s_nop 0
	v_mul_f32_e32 v224, 0.5, v224
	v_pk_mul_f32 v[208:209], v[224:225], v[208:209] op_sel_hi:[0,1]
	v_pk_mul_f32 v[210:211], v[224:225], v[210:211] op_sel_hi:[0,1]
	v_pk_mul_f32 v[212:213], v[224:225], v[212:213] op_sel_hi:[0,1]
	v_pk_mul_f32 v[214:215], v[224:225], v[214:215] op_sel_hi:[0,1]
	v_pk_mul_f32 v[216:217], v[224:225], v[216:217] op_sel_hi:[0,1]
	v_pk_mul_f32 v[218:219], v[224:225], v[218:219] op_sel_hi:[0,1]
	v_pk_mul_f32 v[220:221], v[224:225], v[220:221] op_sel_hi:[0,1]
	v_pk_mul_f32 v[222:223], v[224:225], v[222:223] op_sel_hi:[0,1]
	v_pk_fma_f32 v[192:193], v[0:1], v[208:209], v[192:193]
	v_pk_fma_f32 v[194:195], v[2:3], v[210:211], v[194:195]
	v_pk_fma_f32 v[196:197], v[4:5], v[212:213], v[196:197]
	v_pk_fma_f32 v[198:199], v[6:7], v[214:215], v[198:199]
	v_pk_fma_f32 v[200:201], v[8:9], v[216:217], v[200:201]
	v_pk_fma_f32 v[202:203], v[10:11], v[218:219], v[202:203]
	v_pk_fma_f32 v[204:205], v[12:13], v[220:221], v[204:205]
	v_pk_fma_f32 v[206:207], v[14:15], v[222:223], v[206:207]
	s_add_u32 s20, s20, 0x600000
	s_addc_u32 s21, s21, 0
	global_store_dwordx4 v19, v[192:195], s[20:21] offset:0 nt
	global_store_dwordx4 v19, v[196:199], s[20:21] offset:1024 nt
	global_store_dwordx4 v19, v[200:203], s[20:21] offset:2048 nt
	global_store_dwordx4 v19, v[204:207], s[20:21] offset:3072 nt
	s_waitcnt vmcnt(20)
	v_lshlrev_b32_e32 v208, 16, v120
	v_and_b32_e32 v209, 0xffff0000, v120
	v_lshlrev_b32_e32 v210, 16, v121
	v_and_b32_e32 v211, 0xffff0000, v121
	v_lshlrev_b32_e32 v212, 16, v122
	v_and_b32_e32 v213, 0xffff0000, v122
	v_lshlrev_b32_e32 v214, 16, v123
	v_and_b32_e32 v215, 0xffff0000, v123
	v_lshlrev_b32_e32 v216, 16, v124
	v_and_b32_e32 v217, 0xffff0000, v124
	v_lshlrev_b32_e32 v218, 16, v125
	v_and_b32_e32 v219, 0xffff0000, v125
	v_lshlrev_b32_e32 v220, 16, v126
	v_and_b32_e32 v221, 0xffff0000, v126
	v_lshlrev_b32_e32 v222, 16, v127
	v_and_b32_e32 v223, 0xffff0000, v127
	v_pk_mul_f32 v[224:225], v[208:209], v[208:209]
	v_pk_fma_f32 v[224:225], v[210:211], v[210:211], v[224:225]
	v_pk_fma_f32 v[224:225], v[212:213], v[212:213], v[224:225]
	v_pk_fma_f32 v[224:225], v[214:215], v[214:215], v[224:225]
	v_pk_fma_f32 v[224:225], v[216:217], v[216:217], v[224:225]
	v_pk_fma_f32 v[224:225], v[218:219], v[218:219], v[224:225]
	v_pk_fma_f32 v[224:225], v[220:221], v[220:221], v[224:225]
	v_pk_fma_f32 v[224:225], v[222:223], v[222:223], v[224:225]
	v_add_f32_e32 v224, v224, v225
	v_lshlrev_b32_e32 v192, 16, v112
	v_and_b32_e32 v193, 0xffff0000, v112
	v_lshlrev_b32_e32 v194, 16, v113
	v_and_b32_e32 v195, 0xffff0000, v113
	v_add_f32_dpp v224, v224, v224 quad_perm:[1,0,3,2] row_mask:0xf bank_mask:0xf bound_ctrl:1
	v_lshlrev_b32_e32 v196, 16, v114
	v_and_b32_e32 v197, 0xffff0000, v114
	v_lshlrev_b32_e32 v198, 16, v115
	v_and_b32_e32 v199, 0xffff0000, v115
	v_add_f32_dpp v224, v224, v224 quad_perm:[2,3,0,1] row_mask:0xf bank_mask:0xf bound_ctrl:1
	v_lshlrev_b32_e32 v200, 16, v116
	v_and_b32_e32 v201, 0xffff0000, v116
	v_lshlrev_b32_e32 v202, 16, v117
	v_and_b32_e32 v203, 0xffff0000, v117
	v_add_f32_dpp v224, v224, v224 row_half_mirror row_mask:0xf bank_mask:0xf bound_ctrl:1
	v_lshlrev_b32_e32 v204, 16, v118
	v_and_b32_e32 v205, 0xffff0000, v118
	v_lshlrev_b32_e32 v206, 16, v119
	v_and_b32_e32 v207, 0xffff0000, v119
	v_add_f32_dpp v224, v224, v224 row_mirror row_mask:0xf bank_mask:0xf bound_ctrl:1
	s_nop 0
	v_readlane_b32 s16, v224, 0
	v_readlane_b32 s17, v224, 16
	v_readlane_b32 s18, v224, 32
	v_readlane_b32 s19, v224, 48
	s_nop 1
	v_mov_b32_e32 v224, s17
	v_add_f32_e32 v224, s16, v224
	v_add_f32_e32 v224, s18, v224
	v_add_f32_e32 v224, s19, v224
	v_fmamk_f32 v224, v224, 0x3a800000, v226
	v_rsq_f32_e32 v224, v224
	s_nop 0
	v_mul_f32_e32 v224, 0.5, v224
	v_pk_mul_f32 v[208:209], v[224:225], v[208:209] op_sel_hi:[0,1]
	v_pk_mul_f32 v[210:211], v[224:225], v[210:211] op_sel_hi:[0,1]
	v_pk_mul_f32 v[212:213], v[224:225], v[212:213] op_sel_hi:[0,1]
	v_pk_mul_f32 v[214:215], v[224:225], v[214:215] op_sel_hi:[0,1]
	v_pk_mul_f32 v[216:217], v[224:225], v[216:217] op_sel_hi:[0,1]
	v_pk_mul_f32 v[218:219], v[224:225], v[218:219] op_sel_hi:[0,1]
	v_pk_mul_f32 v[220:221], v[224:225], v[220:221] op_sel_hi:[0,1]
	v_pk_mul_f32 v[222:223], v[224:225], v[222:223] op_sel_hi:[0,1]
	v_pk_fma_f32 v[192:193], v[0:1], v[208:209], v[192:193]
	v_pk_fma_f32 v[194:195], v[2:3], v[210:211], v[194:195]
	v_pk_fma_f32 v[196:197], v[4:5], v[212:213], v[196:197]
	v_pk_fma_f32 v[198:199], v[6:7], v[214:215], v[198:199]
	v_pk_fma_f32 v[200:201], v[8:9], v[216:217], v[200:201]
	v_pk_fma_f32 v[202:203], v[10:11], v[218:219], v[202:203]
	v_pk_fma_f32 v[204:205], v[12:13], v[220:221], v[204:205]
	v_pk_fma_f32 v[206:207], v[14:15], v[222:223], v[206:207]
	s_add_u32 s20, s20, 0x600000
	s_addc_u32 s21, s21, 0
	global_store_dwordx4 v19, v[192:195], s[20:21] offset:0 nt
	global_store_dwordx4 v19, v[196:199], s[20:21] offset:1024 nt
	global_store_dwordx4 v19, v[200:203], s[20:21] offset:2048 nt
	global_store_dwordx4 v19, v[204:207], s[20:21] offset:3072 nt
	s_branch .Lp13_join
; __device__ __forceinline__ unsigned cvt_pk_bf16(float lo, float hi) { const f32x2_t v = {lo, hi}; const bf16x2_t b = __builtin_convertvector(v, bf16x2_t); return __builtin_bit_cast(unsigned, b); }
; __device__ __forceinline__ float lo_bf(unsigned x) { return __uint_as_float(x << 16); }
; __device__ __forceinline__ float hi_bf(unsigned x) { return __uint_as_float(x & 0xffff0000u); }
; __device__ __forceinline__ void rows_proc(PR P, const int mode, const int row, const int lane, float4 (&xv)[4], const float4 (&fo)[4], const float4 (&gp)[4], const float4 (&gn)[4]) {
;     bf16_t* XN = (bf16_t*)(P.ws + WS_XN);
;     if (mode != 0) {
;         float ss = 0.f;
; #pragma unroll
;         for (int q = 0; q < 4; ++q) ss += fo[q].x * fo[q].x + fo[q].y * fo[q].y + fo[q].z * fo[q].z + fo[q].w * fo[q].w;
;         ss = wave_sum(ss); const float r = rsqrtf(ss * (1.0f / 1024.0f) + 1e-6f) * (mode == 2 ? 1.0f : 0.5f);
; #pragma unroll
;         for (int q = 0; q < 4; ++q) {
;             xv[q].x += fo[q].x * r * gp[q].x; xv[q].y += fo[q].y * r * gp[q].y; xv[q].z += fo[q].z * r * gp[q].z; xv[q].w += fo[q].w * r * gp[q].w;
;             if (mode == 3) { const f32x4 t_ = {xv[q].x, xv[q].y, xv[q].z, xv[q].w}; __builtin_nontemporal_store(t_, (f32x4*)(P.out + (size_t)row * 1024 + (q * 64 + lane) * 4)); }
;             else { bf16_t* xo = (mode == 1 ? (bf16_t*)P.out : (bf16_t*)(P.ws + WS_FO + 34603008)) + (size_t)row * 1024; u32x2 t; t.x = pg8::cvt_pk_bf16(xv[q].x, xv[q].y); t.y = pg8::cvt_pk_bf16(xv[q].z, xv[q].w);
;                 __builtin_nontemporal_store(t, (u32x2*)(xo + (q * 64 + lane) * 4)); } }
;         if (mode == 3) return;
; __device__ __forceinline__ void rows_phase(PR P, const int mode, LAS float* ldsf, const int wv) {
;     ...
;         for (int row = gw; row < MP; row += nw) {
;             const int nrow = row + nw < MP ? row + nw : last;
;             rows_load(P, mode, nrow, lane, N);
;             float4 xv[4], fo[4];
; #pragma unroll
;             for (int q = 0; q < 4; ++q) {
;                 xv[q] = mode <= 1 ? R.xf[q] : make_float4(lo_bf(R.xb[q].x), hi_bf(R.xb[q].x), lo_bf(R.xb[q].y), hi_bf(R.xb[q].y));
;                 fo[q] = make_float4(lo_bf(R.fb[q].x), hi_bf(R.fb[q].x), lo_bf(R.fb[q].y), hi_bf(R.fb[q].y)); }
;             rows_proc(P, mode, row, lane, xv, fo, gp, gn);
;             R = N;
;         }
.Lp13_low:
	global_load_dwordx4 v[0:3], v16, s[4:5]
	global_load_dwordx4 v[4:7], v16, s[4:5] offset:1024
	global_load_dwordx4 v[8:11], v16, s[4:5] offset:2048
	global_load_dwordx4 v[12:15], v16, s[4:5] offset:3072
	s_load_dwordx4 s[0:3], s[38:39], 0xd0
	s_lshr_b32 s22, s33, 6
	s_add_i32 s22, s22, s73
	s_add_u32 s22, s22, 15360
	s_lshl_b32 s23, s22, 11
	v_lshl_add_u32 v18, v43, 3, s23
	s_lshl_b32 s23, s22, 12
	v_lshl_add_u32 v19, v43, 4, s23
	v_mov_b32_e32 v226, 0x358637bd
	s_waitcnt lgkmcnt(0)
	s_add_u32 s8, s2, 0xb904800
	s_addc_u32 s9, s3, 0
	s_add_u32 s10, s2, 0x9804800
	s_addc_u32 s11, s3, 0
	s_mov_b64 s[12:13], s[8:9]
	s_mov_b64 s[14:15], s[10:11]
	global_load_dwordx2 v[64:65], v18, s[12:13] offset:0 nt
	global_load_dwordx2 v[66:67], v18, s[12:13] offset:512 nt
	global_load_dwordx2 v[68:69], v18, s[12:13] offset:1024 nt
	global_load_dwordx2 v[70:71], v18, s[12:13] offset:1536 nt
	global_load_dwordx2 v[72:73], v18, s[14:15] offset:0 nt
	global_load_dwordx2 v[74:75], v18, s[14:15] offset:512 nt
	global_load_dwordx2 v[76:77], v18, s[14:15] offset:1024 nt
	global_load_dwordx2 v[78:79], v18, s[14:15] offset:1536 nt
	s_add_u32 s12, s12, 0x100000
	s_addc_u32 s13, s13, 0
	s_add_u32 s14, s14, 0x100000
	s_addc_u32 s15, s15, 0
	global_load_dwordx2 v[80:81], v18, s[12:13] offset:0 nt
	global_load_dwordx2 v[82:83], v18, s[12:13] offset:512 nt
	global_load_dwordx2 v[84:85], v18, s[12:13] offset:1024 nt
	global_load_dwordx2 v[86:87], v18, s[12:13] offset:1536 nt
	global_load_dwordx2 v[88:89], v18, s[14:15] offset:0 nt
	global_load_dwordx2 v[90:91], v18, s[14:15] offset:512 nt
	global_load_dwordx2 v[92:93], v18, s[14:15] offset:1024 nt
	global_load_dwordx2 v[94:95], v18, s[14:15] offset:1536 nt
	s_waitcnt vmcnt(8)
	v_lshlrev_b32_e32 v208, 16, v72
	v_and_b32_e32 v209, 0xffff0000, v72
	v_lshlrev_b32_e32 v210, 16, v73
	v_and_b32_e32 v211, 0xffff0000, v73
	v_lshlrev_b32_e32 v212, 16, v74
	v_and_b32_e32 v213, 0xffff0000, v74
	v_lshlrev_b32_e32 v214, 16, v75
	v_and_b32_e32 v215, 0xffff0000, v75
	v_lshlrev_b32_e32 v216, 16, v76
	v_and_b32_e32 v217, 0xffff0000, v76
	v_lshlrev_b32_e32 v218, 16, v77
	v_and_b32_e32 v219, 0xffff0000, v77
	v_lshlrev_b32_e32 v220, 16, v78
	v_and_b32_e32 v221, 0xffff0000, v78
	v_lshlrev_b32_e32 v222, 16, v79
	v_and_b32_e32 v223, 0xffff0000, v79
	v_pk_mul_f32 v[224:225], v[208:209], v[208:209]
	v_pk_fma_f32 v[224:225], v[210:211], v[210:211], v[224:225]
	v_pk_fma_f32 v[224:225], v[212:213], v[212:213], v[224:225]
	v_pk_fma_f32 v[224:225], v[214:215], v[214:215], v[224:225]
	v_pk_fma_f32 v[224:225], v[216:217], v[216:217], v[224:225]
	v_pk_fma_f32 v[224:225], v[218:219], v[218:219], v[224:225]
	v_pk_fma_f32 v[224:225], v[220:221], v[220:221], v[224:225]
	v_pk_fma_f32 v[224:225], v[222:223], v[222:223], v[224:225]
	v_add_f32_e32 v224, v224, v225
	v_lshlrev_b32_e32 v192, 16, v64
	v_and_b32_e32 v193, 0xffff0000, v64
	v_lshlrev_b32_e32 v194, 16, v65
	v_and_b32_e32 v195, 0xffff0000, v65
	v_add_f32_dpp v224, v224, v224 quad_perm:[1,0,3,2] row_mask:0xf bank_mask:0xf bound_ctrl:1
	v_lshlrev_b32_e32 v196, 16, v66
	v_and_b32_e32 v197, 0xffff0000, v66
	v_lshlrev_b32_e32 v198, 16, v67
	v_and_b32_e32 v199, 0xffff0000, v67
	v_add_f32_dpp v224, v224, v224 quad_perm:[2,3,0,1] row_mask:0xf bank_mask:0xf bound_ctrl:1
	v_lshlrev_b32_e32 v200, 16, v68
	v_and_b32_e32 v201, 0xffff0000, v68
	v_lshlrev_b32_e32 v202, 16, v69
	v_and_b32_e32 v203, 0xffff0000, v69
	v_add_f32_dpp v224, v224, v224 row_half_mirror row_mask:0xf bank_mask:0xf bound_ctrl:1
	v_lshlrev_b32_e32 v204, 16, v70
	v_and_b32_e32 v205, 0xffff0000, v70
	v_lshlrev_b32_e32 v206, 16, v71
	v_and_b32_e32 v207, 0xffff0000, v71
	v_add_f32_dpp v224, v224, v224 row_mirror row_mask:0xf bank_mask:0xf bound_ctrl:1
	s_nop 0
	v_readlane_b32 s16, v224, 0
	v_readlane_b32 s17, v224, 16
	v_readlane_b32 s18, v224, 32
	v_readlane_b32 s19, v224, 48
	s_nop 1
	v_mov_b32_e32 v224, s17
	v_add_f32_e32 v224, s16, v224
	v_add_f32_e32 v224, s18, v224
	v_add_f32_e32 v224, s19, v224
	v_fmamk_f32 v224, v224, 0x3a800000, v226
	v_rsq_f32_e32 v224, v224
	s_nop 0
	v_mul_f32_e32 v224, 0.5, v224
	v_pk_mul_f32 v[208:209], v[224:225], v[208:209] op_sel_hi:[0,1]
	v_pk_mul_f32 v[210:211], v[224:225], v[210:211] op_sel_hi:[0,1]
	v_pk_mul_f32 v[212:213], v[224:225], v[212:213] op_sel_hi:[0,1]
	v_pk_mul_f32 v[214:215], v[224:225], v[214:215] op_sel_hi:[0,1]
	v_pk_mul_f32 v[216:217], v[224:225], v[216:217] op_sel_hi:[0,1]
	v_pk_mul_f32 v[218:219], v[224:225], v[218:219] op_sel_hi:[0,1]
	v_pk_mul_f32 v[220:221], v[224:225], v[220:221] op_sel_hi:[0,1]
	v_pk_mul_f32 v[222:223], v[224:225], v[222:223] op_sel_hi:[0,1]
	v_pk_fma_f32 v[192:193], v[0:1], v[208:209], v[192:193]
	v_pk_fma_f32 v[194:195], v[2:3], v[210:211], v[194:195]
	v_pk_fma_f32 v[196:197], v[4:5], v[212:213], v[196:197]
	v_pk_fma_f32 v[198:199], v[6:7], v[214:215], v[198:199]
	v_pk_fma_f32 v[200:201], v[8:9], v[216:217], v[200:201]
	v_pk_fma_f32 v[202:203], v[10:11], v[218:219], v[202:203]
	v_pk_fma_f32 v[204:205], v[12:13], v[220:221], v[204:205]
	v_pk_fma_f32 v[206:207], v[14:15], v[222:223], v[206:207]
	s_mov_b64 s[20:21], s[0:1]
	global_store_dwordx4 v19, v[192:195], s[20:21] offset:0 nt
	global_store_dwordx4 v19, v[196:199], s[20:21] offset:1024 nt
	global_store_dwordx4 v19, v[200:203], s[20:21] offset:2048 nt
	global_store_dwordx4 v19, v[204:207], s[20:21] offset:3072 nt
	s_waitcnt vmcnt(4)
; __device__ __forceinline__ unsigned cvt_pk_bf16(float lo, float hi) { const f32x2_t v = {lo, hi}; const bf16x2_t b = __builtin_convertvector(v, bf16x2_t); return __builtin_bit_cast(unsigned, b); }
; __device__ __forceinline__ float lo_bf(unsigned x) { return __uint_as_float(x << 16); }
; __device__ __forceinline__ void rows_proc(PR P, const int mode, const int row, const int lane, float4 (&xv)[4], const float4 (&fo)[4], const float4 (&gp)[4], const float4 (&gn)[4]) {
;     bf16_t* XN = (bf16_t*)(P.ws + WS_XN);
;     if (mode != 0) {
;         float ss = 0.f;
; #pragma unroll
;         for (int q = 0; q < 4; ++q) ss += fo[q].x * fo[q].x + fo[q].y * fo[q].y + fo[q].z * fo[q].z + fo[q].w * fo[q].w;
;         ss = wave_sum(ss); const float r = rsqrtf(ss * (1.0f / 1024.0f) + 1e-6f) * (mode == 2 ? 1.0f : 0.5f);
; #pragma unroll
;         for (int q = 0; q < 4; ++q) {
;             xv[q].x += fo[q].x * r * gp[q].x; xv[q].y += fo[q].y * r * gp[q].y; xv[q].z += fo[q].z * r * gp[q].z; xv[q].w += fo[q].w * r * gp[q].w;
;             if (mode == 3) { const f32x4 t_ = {xv[q].x, xv[q].y, xv[q].z, xv[q].w}; __builtin_nontemporal_store(t_, (f32x4*)(P.out + (size_t)row * 1024 + (q * 64 + lane) * 4)); }
;             else { bf16_t* xo = (mode == 1 ? (bf16_t*)P.out : (bf16_t*)(P.ws + WS_FO + 34603008)) + (size_t)row * 1024; u32x2 t; t.x = pg8::cvt_pk_bf16(xv[q].x, xv[q].y); t.y = pg8::cvt_pk_bf16(xv[q].z, xv[q].w);
;                 __builtin_nontemporal_store(t, (u32x2*)(xo + (q * 64 + lane) * 4)); } }
;         if (mode == 3) return;
; __device__ __forceinline__ void rows_phase(PR P, const int mode, LAS float* ldsf, const int wv) {
;     ...
;     if (gw < MP) {
;         const int last = gw + ((MP - 1 - gw) / nw) * nw;
;         RowRaw R, N;
;         rows_load(P, mode, gw, lane, R);
;         for (int row = gw; row < MP; row += nw) {
;             const int nrow = row + nw < MP ? row + nw : last;
;             rows_load(P, mode, nrow, lane, N);
;             float4 xv[4], fo[4];
; #pragma unroll
;             for (int q = 0; q < 4; ++q) {
;                 xv[q] = mode <= 1 ? R.xf[q] : make_float4(lo_bf(R.xb[q].x), hi_bf(R.xb[q].x), lo_bf(R.xb[q].y), hi_bf(R.xb[q].y));
;                 fo[q] = make_float4(lo_bf(R.fb[q].x), hi_bf(R.fb[q].x), lo_bf(R.fb[q].y), hi_bf(R.fb[q].y)); }
;             rows_proc(P, mode, row, lane, xv, fo, gp, gn);
;             R = N;
;         }
;     }
	v_lshlrev_b32_e32 v208, 16, v88
	v_and_b32_e32 v209, 0xffff0000, v88
	v_lshlrev_b32_e32 v210, 16, v89
	v_and_b32_e32 v211, 0xffff0000, v89
	v_lshlrev_b32_e32 v212, 16, v90
	v_and_b32_e32 v213, 0xffff0000, v90
	v_lshlrev_b32_e32 v214, 16, v91
	v_and_b32_e32 v215, 0xffff0000, v91
	v_lshlrev_b32_e32 v216, 16, v92
	v_and_b32_e32 v217, 0xffff0000, v92
	v_lshlrev_b32_e32 v218, 16, v93
	v_and_b32_e32 v219, 0xffff0000, v93
	v_lshlrev_b32_e32 v220, 16, v94
	v_and_b32_e32 v221, 0xffff0000, v94
	v_lshlrev_b32_e32 v222, 16, v95
	v_and_b32_e32 v223, 0xffff0000, v95
	v_pk_mul_f32 v[224:225], v[208:209], v[208:209]
	v_pk_fma_f32 v[224:225], v[210:211], v[210:211], v[224:225]
	v_pk_fma_f32 v[224:225], v[212:213], v[212:213], v[224:225]
	v_pk_fma_f32 v[224:225], v[214:215], v[214:215], v[224:225]
	v_pk_fma_f32 v[224:225], v[216:217], v[216:217], v[224:225]
	v_pk_fma_f32 v[224:225], v[218:219], v[218:219], v[224:225]
	v_pk_fma_f32 v[224:225], v[220:221], v[220:221], v[224:225]
	v_pk_fma_f32 v[224:225], v[222:223], v[222:223], v[224:225]
	v_add_f32_e32 v224, v224, v225
	v_lshlrev_b32_e32 v192, 16, v80
	v_and_b32_e32 v193, 0xffff0000, v80
	v_lshlrev_b32_e32 v194, 16, v81
	v_and_b32_e32 v195, 0xffff0000, v81
	v_add_f32_dpp v224, v224, v224 quad_perm:[1,0,3,2] row_mask:0xf bank_mask:0xf bound_ctrl:1
	v_lshlrev_b32_e32 v196, 16, v82
	v_and_b32_e32 v197, 0xffff0000, v82
	v_lshlrev_b32_e32 v198, 16, v83
	v_and_b32_e32 v199, 0xffff0000, v83
	v_add_f32_dpp v224, v224, v224 quad_perm:[2,3,0,1] row_mask:0xf bank_mask:0xf bound_ctrl:1
	v_lshlrev_b32_e32 v200, 16, v84
	v_and_b32_e32 v201, 0xffff0000, v84
	v_lshlrev_b32_e32 v202, 16, v85
	v_and_b32_e32 v203, 0xffff0000, v85
	v_add_f32_dpp v224, v224, v224 row_half_mirror row_mask:0xf bank_mask:0xf bound_ctrl:1
	v_lshlrev_b32_e32 v204, 16, v86
	v_and_b32_e32 v205, 0xffff0000, v86
	v_lshlrev_b32_e32 v206, 16, v87
	v_and_b32_e32 v207, 0xffff0000, v87
	v_add_f32_dpp v224, v224, v224 row_mirror row_mask:0xf bank_mask:0xf bound_ctrl:1
	s_nop 0
	v_readlane_b32 s16, v224, 0
	v_readlane_b32 s17, v224, 16
	v_readlane_b32 s18, v224, 32
	v_readlane_b32 s19, v224, 48
	s_nop 1
	v_mov_b32_e32 v224, s17
	v_add_f32_e32 v224, s16, v224
	v_add_f32_e32 v224, s18, v224
	v_add_f32_e32 v224, s19, v224
	v_fmamk_f32 v224, v224, 0x3a800000, v226
	v_rsq_f32_e32 v224, v224
	s_nop 0
	v_mul_f32_e32 v224, 0.5, v224
	v_pk_mul_f32 v[208:209], v[224:225], v[208:209] op_sel_hi:[0,1]
	v_pk_mul_f32 v[210:211], v[224:225], v[210:211] op_sel_hi:[0,1]
	v_pk_mul_f32 v[212:213], v[224:225], v[212:213] op_sel_hi:[0,1]
	v_pk_mul_f32 v[214:215], v[224:225], v[214:215] op_sel_hi:[0,1]
	v_pk_mul_f32 v[216:217], v[224:225], v[216:217] op_sel_hi:[0,1]
	v_pk_mul_f32 v[218:219], v[224:225], v[218:219] op_sel_hi:[0,1]
	v_pk_mul_f32 v[220:221], v[224:225], v[220:221] op_sel_hi:[0,1]
	v_pk_mul_f32 v[222:223], v[224:225], v[222:223] op_sel_hi:[0,1]
	v_pk_fma_f32 v[192:193], v[0:1], v[208:209], v[192:193]
	v_pk_fma_f32 v[194:195], v[2:3], v[210:211], v[194:195]
	v_pk_fma_f32 v[196:197], v[4:5], v[212:213], v[196:197]
	v_pk_fma_f32 v[198:199], v[6:7], v[214:215], v[198:199]
	v_pk_fma_f32 v[200:201], v[8:9], v[216:217], v[200:201]
	v_pk_fma_f32 v[202:203], v[10:11], v[218:219], v[202:203]
	v_pk_fma_f32 v[204:205], v[12:13], v[220:221], v[204:205]
	v_pk_fma_f32 v[206:207], v[14:15], v[222:223], v[206:207]
	s_add_u32 s20, s20, 0x200000
	s_addc_u32 s21, s21, 0
	global_store_dwordx4 v19, v[192:195], s[20:21] offset:0 nt
	global_store_dwordx4 v19, v[196:199], s[20:21] offset:1024 nt
	global_store_dwordx4 v19, v[200:203], s[20:21] offset:2048 nt
	global_store_dwordx4 v19, v[204:207], s[20:21] offset:3072 nt
.Lp13_join:
.LBB0_1139:
	s_or_b64 exec, exec, s[6:7]
	s_cmp_lg_u32 s33, 0
	s_cbranch_scc1 .Lseam_G_done
	s_load_dwordx2 s[98:99], s[38:39], 0xd8
	v_mov_b32_e32 v0, 0x3900
	s_mov_b32 s100, 0
	s_waitcnt lgkmcnt(0)
.Lseam_pollG:
	global_load_dword v1, v0, s[98:99] sc1
	s_add_u32 s100, s100, 1
	s_waitcnt vmcnt(0)
	v_readfirstlane_b32 s101, v1
	s_cmp_ge_u32 s101, 64
	s_cbranch_scc1 .Lseam_G_ok
	s_cmp_lt_u32 s100, 0x4000
	s_cbranch_scc1 .Lseam_pollG

; __device__ __forceinline__ float lo_bf(unsigned x) { return __uint_as_float(x << 16); }
; __device__ __forceinline__ float hi_bf(unsigned x) { return __uint_as_float(x & 0xffff0000u); }
; __device__ __forceinline__ void rows_phase(PR P, const int mode, LAS float* ldsf, const int wv) {
;     ...
;     {
;         const int wid = tid >> 6, q = wid & 3, row = MP + 2 * (int)blockIdx.x + (wid >> 2), col = q * 256 + lane * 4;
;         const bool act = row < MT;
;         float4 xv = make_float4(0.f, 0.f, 0.f, 0.f), fo = xv;
;         if (act) {
;             if (mode <= 1) xv = *(const float4*)(P.x_sample + (size_t)(row - MP) * 1024 + col);
;             else { const u32x2 tb = *(const u32x2*)((mode == 2 ? (const bf16_t*)P.out : (const bf16_t*)(P.ws + WS_FO + 34603008)) + (size_t)row * 1024 + col); xv = make_float4(lo_bf(tb.x), hi_bf(tb.x), lo_bf(tb.y), hi_bf(tb.y)); }
;             if (mode != 0) { const int KS = mode == 2 ? 4 : 8; const float* sl = (const float*)(P.ws + WS_OMD) + (size_t)((((row - MP) >> 8) * 4 + q) * KS) * 65536 + (size_t)(row & 255) * 256 + lane * 4;
;                 float4 a = *(const float4*)sl;
;                 for (int p = 1; p < KS; ++p) { const float4 b = *(const float4*)(sl + (size_t)p * 65536); a.x += b.x; a.y += b.y; a.z += b.z; a.w += b.w; }
;                 fo = a; }
.Lseam_G_done:
	s_barrier
	v_ashrrev_i32_e32 v0, 8, v17
	v_add_u32_e32 v11, s90, v0
	v_bfe_u32 v12, v17, 6, 2
	v_add_u32_e32 v0, 0x4000, v11
	s_movk_i32 s0, 0x4200
	v_mov_b32_e32 v2, 0
	v_lshl_or_b32 v10, v12, 8, v44
	v_cmp_gt_i32_e64 s[0:1], s0, v0
	v_ashrrev_i32_e32 v1, 31, v0
	v_mov_b32_e32 v3, 0
	v_mov_b32_e32 v6, 0
	v_mov_b32_e32 v7, v2
	v_mov_b32_e32 v4, 0
	v_mov_b32_e32 v5, 0
	v_mov_b32_e32 v8, 0
	v_mov_b32_e32 v9, v2
	s_and_saveexec_b64 s[2:3], s[0:1]
	s_cbranch_execz .LBB0_1141
	s_load_dwordx2 s[6:7], s[38:39], 0xd8
	v_lshlrev_b64 v[2:3], 11, v[0:1]
	v_lshlrev_b32_e32 v4, 1, v10
	v_mov_b32_e32 v5, 0
	s_mov_b32 s8, 0x1ffffffc
	s_waitcnt lgkmcnt(0)
	v_lshl_add_u64 v[2:3], s[6:7], 0, v[2:3]
	v_lshl_add_u64 v[2:3], v[2:3], 0, v[4:5]
	v_ashrrev_i32_e32 v4, 6, v11
	v_and_or_b32 v4, v4, s8, v12
	v_lshlrev_b32_e32 v6, 3, v4
	v_ashrrev_i32_e32 v7, 31, v6
	v_lshlrev_b64 v[6:7], 18, v[6:7]
	v_lshlrev_b32_e32 v4, 10, v11
	v_lshl_add_u64 v[6:7], s[6:7], 0, v[6:7]
	v_and_b32_e32 v4, 0x3fc00, v4
	v_add_co_u32_e32 v2, vcc, 0xb904000, v2
	v_lshl_add_u64 v[6:7], v[6:7], 0, v[4:5]
	v_mov_b32_e32 v17, v5
	v_addc_co_u32_e32 v3, vcc, 0, v3, vcc
	v_lshl_add_u64 v[4:5], v[6:7], 0, v[16:17]
	s_mov_b32 s6, 0xda04000
	v_add_co_u32_e32 v12, vcc, s6, v4
	s_mov_b32 s6, 0xda44000
	s_nop 0
	v_addc_co_u32_e32 v13, vcc, 0, v5, vcc
	global_load_dwordx2 v[40:41], v[2:3], off offset:2048
	global_load_dwordx4 v[6:9], v[12:13], off offset:2048
	v_add_co_u32_e32 v2, vcc, s6, v4
	s_mov_b32 s6, 0xda84000
	s_nop 0
	v_addc_co_u32_e32 v3, vcc, 0, v5, vcc
	v_add_co_u32_e32 v20, vcc, s6, v4
	s_mov_b32 s6, 0xdac4000
	s_nop 0
	v_addc_co_u32_e32 v21, vcc, 0, v5, vcc
	global_load_dwordx4 v[12:15], v[2:3], off offset:2048
	global_load_dwordx4 v[16:19], v[20:21], off offset:2048
	v_add_co_u32_e32 v2, vcc, s6, v4
	s_mov_b32 s6, 0xdb04000
	s_nop 0
	v_addc_co_u32_e32 v3, vcc, 0, v5, vcc
	v_add_co_u32_e32 v28, vcc, s6, v4
	s_mov_b32 s6, 0xdb44000
	s_nop 0
	v_addc_co_u32_e32 v29, vcc, 0, v5, vcc
	global_load_dwordx4 v[20:23], v[2:3], off offset:2048
	global_load_dwordx4 v[24:27], v[28:29], off offset:2048
	v_add_co_u32_e32 v2, vcc, s6, v4
	s_mov_b32 s6, 0xdb84000
	s_nop 0
	v_addc_co_u32_e32 v3, vcc, 0, v5, vcc
	v_add_co_u32_e32 v36, vcc, s6, v4
	s_mov_b32 s6, 0xdbc4000
	s_nop 0
	v_addc_co_u32_e32 v37, vcc, 0, v5, vcc
	global_load_dwordx4 v[28:31], v[2:3], off offset:2048
	global_load_dwordx4 v[32:35], v[36:37], off offset:2048
	v_add_co_u32_e32 v2, vcc, s6, v4
	s_waitcnt vmcnt(7)
	v_lshlrev_b32_e32 v4, 16, v41
	v_addc_co_u32_e32 v3, vcc, 0, v5, vcc
	global_load_dwordx4 v[36:39], v[2:3], off offset:2048
	v_lshlrev_b32_e32 v2, 16, v40
	v_and_b32_e32 v3, 0xffff0000, v40
	v_and_b32_e32 v5, 0xffff0000, v41
	s_waitcnt vmcnt(6)
	v_pk_add_f32 v[6:7], v[6:7], v[12:13]
	v_pk_add_f32 v[8:9], v[8:9], v[14:15]
	s_waitcnt vmcnt(5)
	v_pk_add_f32 v[6:7], v[6:7], v[16:17]
	v_pk_add_f32 v[8:9], v[8:9], v[18:19]
	s_waitcnt vmcnt(4)
	v_pk_add_f32 v[6:7], v[6:7], v[20:21]
	v_pk_add_f32 v[8:9], v[8:9], v[22:23]
	s_waitcnt vmcnt(3)
	v_pk_add_f32 v[6:7], v[6:7], v[24:25]
	v_pk_add_f32 v[8:9], v[8:9], v[26:27]
	s_waitcnt vmcnt(2)
	v_pk_add_f32 v[6:7], v[6:7], v[28:29]
	v_pk_add_f32 v[8:9], v[8:9], v[30:31]
	s_waitcnt vmcnt(1)
	v_pk_add_f32 v[6:7], v[6:7], v[32:33]
	v_pk_add_f32 v[8:9], v[8:9], v[34:35]
	s_waitcnt vmcnt(0)
	v_pk_add_f32 v[6:7], v[6:7], v[36:37]
	v_pk_add_f32 v[8:9], v[8:9], v[38:39]

; #define LAS __attribute__((address_space(3)))
; #define CAS __attribute__((address_space(4)))
; __global__ void __launch_bounds__(512, 2) hymba_mega(Params P_unused) {
;     extern __shared__ __attribute__((aligned(16))) unsigned char shm[];
;     cg::grid_group grid = cg::this_grid();
;     LAS unsigned char* lds = (LAS unsigned char*)shm; LAS float* ldsf = (LAS float*)shm;
;     const int G = gridDim.x, bx = blockIdx.x;
;     const int wv = __builtin_amdgcn_readfirstlane(threadIdx.x >> 6);
;     const CAS Params* kp = (const CAS Params*)__builtin_amdgcn_kernarg_segment_ptr();
	.amdhsa_kernel _Z10hymba_mega6Params
		.amdhsa_group_segment_fixed_size 0
		.amdhsa_private_segment_fixed_size 0
		.amdhsa_kernarg_size 480
		.amdhsa_user_sgpr_count 2
		.amdhsa_user_sgpr_dispatch_ptr 0
		.amdhsa_user_sgpr_queue_ptr 0
		.amdhsa_user_sgpr_kernarg_segment_ptr 1
		.amdhsa_user_sgpr_dispatch_id 0
		.amdhsa_user_sgpr_kernarg_preload_length 0
		.amdhsa_user_sgpr_kernarg_preload_offset 0
		.amdhsa_user_sgpr_private_segment_size 0
		.amdhsa_uses_dynamic_stack 0
		.amdhsa_enable_private_segment 0
		.amdhsa_system_sgpr_workgroup_id_x 1
		.amdhsa_system_sgpr_workgroup_id_y 0
		.amdhsa_system_sgpr_workgroup_id_z 0
		.amdhsa_system_sgpr_workgroup_info 0
		.amdhsa_system_vgpr_workitem_id 2
		.amdhsa_next_free_vgpr 255
		.amdhsa_next_free_sgpr 102
		.amdhsa_accum_offset 256
		.amdhsa_reserve_vcc 1
		.amdhsa_float_round_mode_32 0
		.amdhsa_float_round_mode_16_64 0
		.amdhsa_float_denorm_mode_32 3
		.amdhsa_float_denorm_mode_16_64 3
		.amdhsa_dx10_clamp 1
		.amdhsa_ieee_mode 1
		.amdhsa_fp16_overflow 0
		.amdhsa_tg_split 0
		.amdhsa_exception_fp_ieee_invalid_op 0
		.amdhsa_exception_fp_denorm_src 0
		.amdhsa_exception_fp_ieee_div_zero 0
		.amdhsa_exception_fp_ieee_overflow 0
		.amdhsa_exception_fp_ieee_underflow 0
		.amdhsa_exception_fp_ieee_inexact 0
		.amdhsa_exception_int_div_zero 0
	.end_amdhsa_kernel

; #define LAS __attribute__((address_space(3)))
; #define CAS __attribute__((address_space(4)))
; __global__ void __launch_bounds__(512, 2) hymba_mega(Params P_unused) {
;     extern __shared__ __attribute__((aligned(16))) unsigned char shm[];
;     cg::grid_group grid = cg::this_grid();
;     LAS unsigned char* lds = (LAS unsigned char*)shm; LAS float* ldsf = (LAS float*)shm;
;     const int G = gridDim.x, bx = blockIdx.x;
;     const int wv = __builtin_amdgcn_readfirstlane(threadIdx.x >> 6);
;     const CAS Params* kp = (const CAS Params*)__builtin_amdgcn_kernarg_segment_ptr();
amdhsa.kernels:
  - .agpr_count:     0
    .args:
      - .offset:         0
        .size:           224
        .value_kind:     by_value
      - .offset:         224
        .size:           4
        .value_kind:     hidden_block_count_x
      - .offset:         228
        .size:           4
        .value_kind:     hidden_block_count_y
      - .offset:         232
        .size:           4
        .value_kind:     hidden_block_count_z
      - .offset:         236
        .size:           2
        .value_kind:     hidden_group_size_x
      - .offset:         238
        .size:           2
        .value_kind:     hidden_group_size_y
      - .offset:         240
        .size:           2
        .value_kind:     hidden_group_size_z
      - .offset:         242
        .size:           2
        .value_kind:     hidden_remainder_x
      - .offset:         244
        .size:           2
        .value_kind:     hidden_remainder_y
      - .offset:         246
        .size:           2
        .value_kind:     hidden_remainder_z
      - .offset:         264
        .size:           8
        .value_kind:     hidden_global_offset_x
      - .offset:         272
        .size:           8
        .value_kind:     hidden_global_offset_y
      - .offset:         280
        .size:           8
        .value_kind:     hidden_global_offset_z
      - .offset:         288
        .size:           2
        .value_kind:     hidden_grid_dims
      - .offset:         312
        .size:           8
        .value_kind:     hidden_multigrid_sync_arg
      - .offset:         344
        .size:           4
        .value_kind:     hidden_dynamic_lds_size
    .group_segment_fixed_size: 0
    .kernarg_segment_align: 8
    .kernarg_segment_size: 480
    .language:       OpenCL C
    .language_version:
      - 2
      - 0
    .max_flat_workgroup_size: 512
    .name:           _Z10hymba_mega6Params
    .private_segment_fixed_size: 0
    .sgpr_count:     108
    .sgpr_spill_count: 18
    .symbol:         _Z10hymba_mega6Params.kd
    .uniform_work_group_size: 1
    .uses_dynamic_stack: false
    .vgpr_count:     255
    .vgpr_spill_count: 0
    .wavefront_size: 64
